# in-proj and gate/up GEMM epilogues: write-through (sc1) stores of the bf16 outputs so the phase-end L2 writeback before the grid barrier is short; compress W2 loads batched
# speedup vs baseline: 1.0402x; 1.0110x over previous
.LBB0_172:
	v_readlane_b32 s40, v253, 4
	v_readlane_b32 s41, v253, 5
	v_lshrrev_b32_e32 v133, 1, v146
	s_load_dwordx2 s[42:43], s[40:41], 0x98
	v_and_b32_e32 v132, 1, v146
	v_lshl_add_u32 v131, s46, 8, v133
	v_lshlrev_b32_e32 v131, 7, v131
	v_lshl_or_b32 v131, v132, 6, v131
	v_lshl_add_u32 v170, s46, 8, v149
	s_waitcnt lgkmcnt(0)
	s_add_u32 s40, s42, 0x1a700000
	s_addc_u32 s41, s43, 0
	global_load_dwordx4 v[236:239], v131, s[40:41]
	global_load_dwordx4 v[240:243], v131, s[40:41] offset:16
	global_load_dwordx4 v[244:247], v131, s[40:41] offset:32
	global_load_dwordx4 v[138:141], v131, s[40:41] offset:48
	s_mov_b32 s11, 0xf800000
	v_ashrrev_i32_e32 v171, 31, v170
	v_or_b32_e32 v176, 16, v170
	v_ashrrev_i32_e32 v177, 31, v176
	v_or_b32_e32 v180, 32, v170
	v_ashrrev_i32_e32 v181, 31, v180
	v_or_b32_e32 v184, 48, v170
	v_ashrrev_i32_e32 v185, 31, v184
	v_add_u32_e32 v188, 0x80, v170
	v_ashrrev_i32_e32 v189, 31, v188
	v_add_u32_e32 v192, 0x90, v170
	v_ashrrev_i32_e32 v193, 31, v192
	v_add_u32_e32 v196, 0xa0, v170
	v_ashrrev_i32_e32 v197, 31, v196
	v_add_u32_e32 v200, 0xb0, v170
	v_ashrrev_i32_e32 v201, 31, v200
	v_lshl_or_b32 v172, s37, 8, v179
	v_ashrrev_i32_e32 v173, 31, v172
	v_lshl_add_u64 v[154:155], v[172:173], 1, s[42:43]
	v_lshlrev_b32_e32 v133, 2, v133
	v_add_u32_e32 v133, 0x20240, v133
	s_waitcnt vmcnt(0)
	v_pk_add_f32 v[238:239], v[238:239], v[242:243]
	v_pk_add_f32 v[236:237], v[236:237], v[240:241]
	v_pk_add_f32 v[246:247], v[246:247], v[140:141]
	v_pk_add_f32 v[244:245], v[244:245], v[138:139]
	s_nop 0
	v_add_f32_e32 v236, v236, v237
	v_add_f32_e32 v238, v238, v239
	v_add_f32_e32 v244, v244, v245
	v_add_f32_e32 v246, v246, v247
	v_add_f32_e32 v236, v236, v238
	v_add_f32_e32 v244, v244, v246
	v_add_f32_e32 v236, v236, v244
	s_nop 1
	v_mov_b32_dpp v237, v236 quad_perm:[1,0,3,2] row_mask:0xf bank_mask:0xf
	s_nop 0
	v_add_f32_e32 v236, v236, v237
	v_fmamk_f32 v134, v236, 0x3a000000, v204
	v_cmp_gt_f32_e32 vcc, s11, v134
	v_mul_f32_e32 v135, 0x4f800000, v134
	s_nop 0
	v_cndmask_b32_e32 v134, v134, v135, vcc
	v_sqrt_f32_e32 v135, v134
	s_nop 0
	v_add_u32_e32 v136, -1, v135
	v_fma_f32 v137, -v136, v135, v134
	v_cmp_ge_f32_e64 s[40:41], 0, v137
	v_add_u32_e32 v137, 1, v135
	s_nop 0
	v_cndmask_b32_e64 v136, v135, v136, s[40:41]
	v_fma_f32 v135, -v137, v135, v134
	v_cmp_lt_f32_e64 s[40:41], 0, v135
	s_nop 1
	v_cndmask_b32_e64 v135, v136, v137, s[40:41]
	v_mul_f32_e32 v136, 0x37800000, v135
	v_cndmask_b32_e32 v135, v135, v136, vcc
	v_cmp_class_f32_e32 vcc, v134, v205
	s_nop 1
	v_cndmask_b32_e32 v134, v135, v134, vcc
	v_div_scale_f32 v135, s[40:41], v134, v134, 1.0
	v_rcp_f32_e32 v136, v135
	s_nop 0
	v_fma_f32 v137, -v135, v136, 1.0
	v_fmac_f32_e32 v136, v137, v136
	v_div_scale_f32 v137, vcc, 1.0, v134, 1.0
	v_mul_f32_e32 v142, v137, v136
	v_fma_f32 v143, -v135, v142, v137
	v_fmac_f32_e32 v142, v143, v136
	v_fma_f32 v135, -v135, v142, v137
	v_div_fmas_f32 v135, v135, v136, v142
	v_div_fixup_f32 v144, v135, v134, 1.0
	ds_write_b32 v133, v144
	v_lshlrev_b32_e32 v132, 2, v149
	v_add_u32_e32 v132, 0x20240, v132
	s_waitcnt lgkmcnt(0)
	s_barrier
	ds_read_b32 v174, v132
	ds_read_b32 v178, v132 offset:64
	ds_read_b32 v182, v132 offset:128
	ds_read_b32 v186, v132 offset:192
	ds_read_b32 v190, v132 offset:512
	ds_read_b32 v194, v132 offset:576
	ds_read_b32 v198, v132 offset:640
	ds_read_b32 v202, v132 offset:704
	s_mov_b32 s11, 0x5d20000
	s_mov_b64 s[40:41], 0x5d20000
	s_waitcnt lgkmcnt(0)
	v_lshl_add_u64 v[130:131], v[172:173], 2, s[42:43]
	v_lshl_add_u64 v[142:143], v[130:131], 0, s[40:41]
	v_add_co_u32_e32 v130, vcc, s11, v130
	s_mov_b64 s[40:41], 0x5f00000
	s_nop 0
	v_addc_co_u32_e32 v131, vcc, 0, v131, vcc
	global_load_dwordx4 v[134:137], v[130:131], off
	global_load_dwordx4 v[138:141], v[142:143], off offset:16
	s_nop 0
	global_load_dwordx4 v[130:133], v[142:143], off offset:528
	s_nop 0
	global_load_dwordx4 v[142:145], v[142:143], off offset:512
	v_lshl_add_u64 v[172:173], v[154:155], 0, s[40:41]
	v_lshlrev_b64 v[154:155], 13, v[170:171]
	v_lshl_add_u64 v[154:155], v[172:173], 0, v[154:155]
	s_mov_b64 s[40:41], -1
	s_andn2_b64 vcc, exec, s[38:39]
	s_waitcnt vmcnt(3)
	v_pk_fma_f32 v[128:129], v[128:129], v[174:175], v[136:137] op_sel_hi:[1,0,1]
	v_pk_fma_f32 v[126:127], v[126:127], v[174:175], v[134:135] op_sel_hi:[1,0,1]
	s_waitcnt vmcnt(2)
	v_pk_fma_f32 v[156:157], v[124:125], v[174:175], v[140:141] op_sel_hi:[1,0,1]
	v_pk_fma_f32 v[124:125], v[122:123], v[174:175], v[138:139] op_sel_hi:[1,0,1]
	v_cvt_pk_bf16_f32 v122, v126, v127
	v_cvt_pk_bf16_f32 v123, v128, v129
	v_cvt_pk_bf16_f32 v124, v124, v125
	v_cvt_pk_bf16_f32 v125, v156, v157
	global_store_dwordx4 v[154:155], v[122:125], off sc1
	s_waitcnt vmcnt(1)
	v_pk_fma_f32 v[116:117], v[116:117], v[174:175], v[144:145] op_sel_hi:[1,0,1]
	v_pk_fma_f32 v[114:115], v[114:115], v[174:175], v[142:143] op_sel_hi:[1,0,1]
	v_pk_fma_f32 v[122:123], v[108:109], v[174:175], v[132:133] op_sel_hi:[1,0,1]
	v_pk_fma_f32 v[108:109], v[106:107], v[174:175], v[130:131] op_sel_hi:[1,0,1]
	v_cvt_pk_bf16_f32 v106, v114, v115
	v_cvt_pk_bf16_f32 v107, v116, v117
	v_cvt_pk_bf16_f32 v108, v108, v109
	v_cvt_pk_bf16_f32 v109, v122, v123
	global_store_dwordx4 v[154:155], v[106:109], off offset:256 sc1
	v_pk_fma_f32 v[112:113], v[112:113], v[178:179], v[140:141] op_sel_hi:[1,0,1]
	v_pk_fma_f32 v[110:111], v[110:111], v[178:179], v[138:139] op_sel_hi:[1,0,1]
	v_lshlrev_b64 v[106:107], 13, v[176:177]
	v_lshl_add_u64 v[114:115], v[172:173], 0, v[106:107]
	v_pk_fma_f32 v[108:109], v[120:121], v[178:179], v[136:137] op_sel_hi:[1,0,1]
	v_pk_fma_f32 v[106:107], v[118:119], v[178:179], v[134:135] op_sel_hi:[1,0,1]
	v_pk_fma_f32 v[100:101], v[100:101], v[178:179], v[144:145] op_sel_hi:[1,0,1]
	v_cvt_pk_bf16_f32 v106, v106, v107
	v_cvt_pk_bf16_f32 v107, v108, v109
	v_cvt_pk_bf16_f32 v108, v110, v111
	v_cvt_pk_bf16_f32 v109, v112, v113
	global_store_dwordx4 v[114:115], v[106:109], off sc1
	v_pk_fma_f32 v[98:99], v[98:99], v[178:179], v[142:143] op_sel_hi:[1,0,1]
	v_pk_fma_f32 v[96:97], v[96:97], v[182:183], v[140:141] op_sel_hi:[1,0,1]
	v_pk_fma_f32 v[106:107], v[92:93], v[178:179], v[132:133] op_sel_hi:[1,0,1]
	v_pk_fma_f32 v[92:93], v[90:91], v[178:179], v[130:131] op_sel_hi:[1,0,1]
	v_cvt_pk_bf16_f32 v90, v98, v99
	v_cvt_pk_bf16_f32 v91, v100, v101
	v_cvt_pk_bf16_f32 v92, v92, v93
	v_cvt_pk_bf16_f32 v93, v106, v107
	global_store_dwordx4 v[114:115], v[90:93], off offset:256 sc1
	v_pk_fma_f32 v[94:95], v[94:95], v[182:183], v[138:139] op_sel_hi:[1,0,1]
	v_pk_fma_f32 v[84:85], v[84:85], v[182:183], v[144:145] op_sel_hi:[1,0,1]
	v_lshlrev_b64 v[90:91], 13, v[180:181]
	v_lshl_add_u64 v[98:99], v[172:173], 0, v[90:91]
	v_pk_fma_f32 v[92:93], v[104:105], v[182:183], v[136:137] op_sel_hi:[1,0,1]
	v_pk_fma_f32 v[90:91], v[102:103], v[182:183], v[134:135] op_sel_hi:[1,0,1]
	v_pk_fma_f32 v[82:83], v[82:83], v[182:183], v[142:143] op_sel_hi:[1,0,1]
	v_cvt_pk_bf16_f32 v90, v90, v91
	v_cvt_pk_bf16_f32 v91, v92, v93
	v_cvt_pk_bf16_f32 v92, v94, v95
	v_cvt_pk_bf16_f32 v93, v96, v97
	global_store_dwordx4 v[98:99], v[90:93], off sc1
	v_pk_fma_f32 v[80:81], v[80:81], v[186:187], v[140:141] op_sel_hi:[1,0,1]
	v_pk_fma_f32 v[78:79], v[78:79], v[186:187], v[138:139] op_sel_hi:[1,0,1]
	v_pk_fma_f32 v[90:91], v[76:77], v[182:183], v[132:133] op_sel_hi:[1,0,1]
	v_pk_fma_f32 v[76:77], v[74:75], v[182:183], v[130:131] op_sel_hi:[1,0,1]
	v_cvt_pk_bf16_f32 v74, v82, v83
	v_cvt_pk_bf16_f32 v75, v84, v85
	v_cvt_pk_bf16_f32 v76, v76, v77
	v_cvt_pk_bf16_f32 v77, v90, v91
	global_store_dwordx4 v[98:99], v[74:77], off offset:256 sc1
	v_pk_fma_f32 v[72:73], v[72:73], v[186:187], v[144:145] op_sel_hi:[1,0,1]
	v_pk_fma_f32 v[70:71], v[70:71], v[186:187], v[142:143] op_sel_hi:[1,0,1]
	v_lshlrev_b64 v[74:75], 13, v[184:185]
	v_lshl_add_u64 v[82:83], v[172:173], 0, v[74:75]
	v_pk_fma_f32 v[76:77], v[88:89], v[186:187], v[136:137] op_sel_hi:[1,0,1]
	v_pk_fma_f32 v[74:75], v[86:87], v[186:187], v[134:135] op_sel_hi:[1,0,1]
	v_pk_fma_f32 v[64:65], v[64:65], v[190:191], v[136:137] op_sel_hi:[1,0,1]
	v_cvt_pk_bf16_f32 v74, v74, v75
	v_cvt_pk_bf16_f32 v75, v76, v77
	v_cvt_pk_bf16_f32 v76, v78, v79
	v_cvt_pk_bf16_f32 v77, v80, v81
	global_store_dwordx4 v[82:83], v[74:77], off sc1
	v_pk_fma_f32 v[62:63], v[62:63], v[190:191], v[134:135] op_sel_hi:[1,0,1]
	v_pk_fma_f32 v[52:53], v[52:53], v[190:191], v[144:145] op_sel_hi:[1,0,1]
	v_pk_fma_f32 v[74:75], v[68:69], v[186:187], v[132:133] op_sel_hi:[1,0,1]
	v_pk_fma_f32 v[68:69], v[66:67], v[186:187], v[130:131] op_sel_hi:[1,0,1]
	v_cvt_pk_bf16_f32 v66, v70, v71
	v_cvt_pk_bf16_f32 v67, v72, v73
	v_cvt_pk_bf16_f32 v68, v68, v69
	v_cvt_pk_bf16_f32 v69, v74, v75
	global_store_dwordx4 v[82:83], v[66:69], off offset:256 sc1
	v_pk_fma_f32 v[50:51], v[50:51], v[190:191], v[142:143] op_sel_hi:[1,0,1]
	v_pk_fma_f32 v[48:49], v[48:49], v[194:195], v[140:141] op_sel_hi:[1,0,1]
	v_lshlrev_b64 v[66:67], 13, v[188:189]
	v_pk_fma_f32 v[68:69], v[60:61], v[190:191], v[140:141] op_sel_hi:[1,0,1]
	v_pk_fma_f32 v[60:61], v[58:59], v[190:191], v[138:139] op_sel_hi:[1,0,1]
	v_lshl_add_u64 v[66:67], v[172:173], 0, v[66:67]
	v_cvt_pk_bf16_f32 v58, v62, v63
	v_cvt_pk_bf16_f32 v59, v64, v65
	v_cvt_pk_bf16_f32 v60, v60, v61
	v_cvt_pk_bf16_f32 v61, v68, v69
	global_store_dwordx4 v[66:67], v[58:61], off sc1
	v_pk_fma_f32 v[46:47], v[46:47], v[194:195], v[138:139] op_sel_hi:[1,0,1]
	v_pk_fma_f32 v[36:37], v[36:37], v[194:195], v[144:145] op_sel_hi:[1,0,1]
	v_pk_fma_f32 v[58:59], v[44:45], v[190:191], v[132:133] op_sel_hi:[1,0,1]
	v_pk_fma_f32 v[44:45], v[42:43], v[190:191], v[130:131] op_sel_hi:[1,0,1]
	v_cvt_pk_bf16_f32 v42, v50, v51
	v_cvt_pk_bf16_f32 v43, v52, v53
	v_cvt_pk_bf16_f32 v44, v44, v45
	v_cvt_pk_bf16_f32 v45, v58, v59
	global_store_dwordx4 v[66:67], v[42:45], off offset:256 sc1
	v_pk_fma_f32 v[34:35], v[34:35], v[194:195], v[142:143] op_sel_hi:[1,0,1]
	v_pk_fma_f32 v[32:33], v[32:33], v[198:199], v[140:141] op_sel_hi:[1,0,1]
	v_lshlrev_b64 v[42:43], 13, v[192:193]
	v_lshl_add_u64 v[50:51], v[172:173], 0, v[42:43]
	v_pk_fma_f32 v[44:45], v[56:57], v[194:195], v[136:137] op_sel_hi:[1,0,1]
	v_pk_fma_f32 v[42:43], v[54:55], v[194:195], v[134:135] op_sel_hi:[1,0,1]
	v_pk_fma_f32 v[30:31], v[30:31], v[198:199], v[138:139] op_sel_hi:[1,0,1]
	v_cvt_pk_bf16_f32 v42, v42, v43
	v_cvt_pk_bf16_f32 v43, v44, v45
	v_cvt_pk_bf16_f32 v44, v46, v47
	v_cvt_pk_bf16_f32 v45, v48, v49
	global_store_dwordx4 v[50:51], v[42:45], off sc1
	v_pk_fma_f32 v[20:21], v[20:21], v[198:199], v[144:145] op_sel_hi:[1,0,1]
	v_pk_fma_f32 v[18:19], v[18:19], v[198:199], v[142:143] op_sel_hi:[1,0,1]
	v_pk_fma_f32 v[42:43], v[28:29], v[194:195], v[132:133] op_sel_hi:[1,0,1]
	v_pk_fma_f32 v[28:29], v[26:27], v[194:195], v[130:131] op_sel_hi:[1,0,1]
	v_cvt_pk_bf16_f32 v26, v34, v35
	v_cvt_pk_bf16_f32 v27, v36, v37
	v_cvt_pk_bf16_f32 v28, v28, v29
	v_cvt_pk_bf16_f32 v29, v42, v43
	global_store_dwordx4 v[50:51], v[26:29], off offset:256 sc1
	v_pk_fma_f32 v[16:17], v[16:17], v[202:203], v[140:141] op_sel_hi:[1,0,1]
	v_pk_fma_f32 v[14:15], v[14:15], v[202:203], v[138:139] op_sel_hi:[1,0,1]
	v_lshlrev_b64 v[26:27], 13, v[196:197]
	v_lshl_add_u64 v[34:35], v[172:173], 0, v[26:27]
	v_pk_fma_f32 v[28:29], v[40:41], v[198:199], v[136:137] op_sel_hi:[1,0,1]
	v_pk_fma_f32 v[26:27], v[38:39], v[198:199], v[134:135] op_sel_hi:[1,0,1]
	v_pk_fma_f32 v[8:9], v[8:9], v[202:203], v[144:145] op_sel_hi:[1,0,1]
	v_cvt_pk_bf16_f32 v26, v26, v27
	v_cvt_pk_bf16_f32 v27, v28, v29
	v_cvt_pk_bf16_f32 v28, v30, v31
	v_cvt_pk_bf16_f32 v29, v32, v33
	global_store_dwordx4 v[34:35], v[26:29], off sc1
	v_pk_fma_f32 v[6:7], v[6:7], v[202:203], v[142:143] op_sel_hi:[1,0,1]
	s_nop 0
	v_pk_fma_f32 v[26:27], v[12:13], v[198:199], v[132:133] op_sel_hi:[1,0,1]
	v_pk_fma_f32 v[12:13], v[10:11], v[198:199], v[130:131] op_sel_hi:[1,0,1]
	v_cvt_pk_bf16_f32 v10, v18, v19
	v_cvt_pk_bf16_f32 v11, v20, v21
	v_cvt_pk_bf16_f32 v12, v12, v13
	v_cvt_pk_bf16_f32 v13, v26, v27
	global_store_dwordx4 v[34:35], v[10:13], off offset:256 sc1
	s_nop 1
	v_lshlrev_b64 v[10:11], 13, v[200:201]
	v_lshl_add_u64 v[18:19], v[172:173], 0, v[10:11]
	v_pk_fma_f32 v[12:13], v[24:25], v[202:203], v[136:137] op_sel_hi:[1,0,1]
	v_pk_fma_f32 v[10:11], v[22:23], v[202:203], v[134:135] op_sel_hi:[1,0,1]
	s_nop 0
	v_cvt_pk_bf16_f32 v10, v10, v11
	v_cvt_pk_bf16_f32 v11, v12, v13
	v_cvt_pk_bf16_f32 v12, v14, v15
	v_cvt_pk_bf16_f32 v13, v16, v17
	global_store_dwordx4 v[18:19], v[10:13], off sc1
	s_nop 1
	v_pk_fma_f32 v[10:11], v[4:5], v[202:203], v[132:133] op_sel_hi:[1,0,1]
	v_pk_fma_f32 v[4:5], v[2:3], v[202:203], v[130:131] op_sel_hi:[1,0,1]
	v_cvt_pk_bf16_f32 v2, v6, v7
	v_cvt_pk_bf16_f32 v3, v8, v9
	v_cvt_pk_bf16_f32 v4, v4, v5
	v_cvt_pk_bf16_f32 v5, v10, v11
	global_store_dwordx4 v[18:19], v[2:5], off offset:256 sc1
	s_cbranch_vccnz .LBB0_161
	s_andn2_b64 vcc, exec, s[6:7]
	s_cbranch_vccnz .LBB0_160
	s_barrier
	s_branch .LBB0_160

.LBB0_270:
	s_or_b64 exec, exec, s[22:23]
	s_and_b64 s[18:19], s[20:21], exec
	s_mov_b32 s14, 0x5b00000
	s_cselect_b32 s16, s14, 0x5c00000
	v_mov_b32_e32 v6, 0
	v_lshl_add_u64 v[10:11], v[130:131], 0, s[16:17]
	s_mov_b64 s[22:23], 0
	v_mov_b32_e32 v0, v230
	v_mov_b32_e32 v16, v228
	v_mov_b32_e32 v7, v6
	v_mov_b32_e32 v8, v6
	v_mov_b32_e32 v9, v6
	v_mov_b32_e32 v2, v6
	v_mov_b32_e32 v3, v6
	v_mov_b32_e32 v4, v6
	v_mov_b32_e32 v5, v6
	s_waitcnt lgkmcnt(0)
	s_barrier
	v_and_b32_e32 v12, 0x70, v228
	v_add_u32_e32 v13, 16, v228
	v_and_b32_e32 v13, 0x70, v13
	v_xad_u32 v114, v128, v12, v230
	v_xad_u32 v115, v129, v12, v230
	v_xad_u32 v116, v128, v13, v230
	v_xad_u32 v117, v129, v13, v230
	s_mov_b64 s[22:23], 0x10000
	v_lshl_add_u64 v[14:15], v[10:11], 0, s[22:23]
	ds_read_b128 v[18:21], v114
	ds_read_b128 v[22:25], v115
	ds_read_b128 v[26:29], v114 offset:128
	ds_read_b128 v[30:33], v115 offset:128
	global_load_dwordx4 v[34:37], v[10:11], off
	global_load_dwordx4 v[38:41], v[14:15], off
	global_load_dwordx4 v[42:45], v[10:11], off offset:64
	global_load_dwordx4 v[46:49], v[14:15], off offset:64
	global_load_dwordx4 v[50:53], v[10:11], off offset:128
	global_load_dwordx4 v[54:57], v[14:15], off offset:128
	global_load_dwordx4 v[58:61], v[10:11], off offset:192
	global_load_dwordx4 v[62:65], v[14:15], off offset:192
	ds_read_b128 v[66:69], v114 offset:256
	ds_read_b128 v[70:73], v115 offset:256
	ds_read_b128 v[74:77], v114 offset:384
	ds_read_b128 v[78:81], v115 offset:384
	global_load_dwordx4 v[82:85], v[10:11], off offset:256
	global_load_dwordx4 v[86:89], v[14:15], off offset:256
	global_load_dwordx4 v[90:93], v[10:11], off offset:320
	global_load_dwordx4 v[94:97], v[14:15], off offset:320
	global_load_dwordx4 v[98:101], v[10:11], off offset:384
	global_load_dwordx4 v[102:105], v[14:15], off offset:384
	global_load_dwordx4 v[106:109], v[10:11], off offset:448
	global_load_dwordx4 v[110:113], v[14:15], off offset:448
	s_waitcnt vmcnt(14) lgkmcnt(7)
	v_mfma_f32_16x16x32_bf16 v[6:9], v[18:21], v[34:37], v[6:9]
	v_mfma_f32_16x16x32_bf16 v[2:5], v[18:21], v[38:41], v[2:5]
	s_waitcnt vmcnt(12) lgkmcnt(6)
	v_mfma_f32_16x16x32_bf16 v[6:9], v[22:25], v[42:45], v[6:9]
	v_mfma_f32_16x16x32_bf16 v[2:5], v[22:25], v[46:49], v[2:5]
	s_waitcnt vmcnt(10) lgkmcnt(5)
	v_mfma_f32_16x16x32_bf16 v[6:9], v[26:29], v[50:53], v[6:9]
	v_mfma_f32_16x16x32_bf16 v[2:5], v[26:29], v[54:57], v[2:5]
	s_waitcnt vmcnt(8) lgkmcnt(4)
	v_mfma_f32_16x16x32_bf16 v[6:9], v[30:33], v[58:61], v[6:9]
	v_mfma_f32_16x16x32_bf16 v[2:5], v[30:33], v[62:65], v[2:5]
	ds_read_b128 v[18:21], v114 offset:512
	ds_read_b128 v[22:25], v115 offset:512
	ds_read_b128 v[26:29], v114 offset:640
	ds_read_b128 v[30:33], v115 offset:640
	global_load_dwordx4 v[34:37], v[10:11], off offset:512
	global_load_dwordx4 v[38:41], v[14:15], off offset:512
	global_load_dwordx4 v[42:45], v[10:11], off offset:576
	global_load_dwordx4 v[46:49], v[14:15], off offset:576
	global_load_dwordx4 v[50:53], v[10:11], off offset:640
	global_load_dwordx4 v[54:57], v[14:15], off offset:640
	global_load_dwordx4 v[58:61], v[10:11], off offset:704
	global_load_dwordx4 v[62:65], v[14:15], off offset:704
	s_waitcnt vmcnt(14) lgkmcnt(7)
	v_mfma_f32_16x16x32_bf16 v[6:9], v[66:69], v[82:85], v[6:9]
	v_mfma_f32_16x16x32_bf16 v[2:5], v[66:69], v[86:89], v[2:5]
	s_waitcnt vmcnt(12) lgkmcnt(6)
	v_mfma_f32_16x16x32_bf16 v[6:9], v[70:73], v[90:93], v[6:9]
	v_mfma_f32_16x16x32_bf16 v[2:5], v[70:73], v[94:97], v[2:5]
	s_waitcnt vmcnt(10) lgkmcnt(5)
	v_mfma_f32_16x16x32_bf16 v[6:9], v[74:77], v[98:101], v[6:9]
	v_mfma_f32_16x16x32_bf16 v[2:5], v[74:77], v[102:105], v[2:5]
	s_waitcnt vmcnt(8) lgkmcnt(4)
	v_mfma_f32_16x16x32_bf16 v[6:9], v[78:81], v[106:109], v[6:9]
	v_mfma_f32_16x16x32_bf16 v[2:5], v[78:81], v[110:113], v[2:5]
	ds_read_b128 v[66:69], v114 offset:768
	ds_read_b128 v[70:73], v115 offset:768
	ds_read_b128 v[74:77], v114 offset:896
	ds_read_b128 v[78:81], v115 offset:896
	global_load_dwordx4 v[82:85], v[10:11], off offset:768
	global_load_dwordx4 v[86:89], v[14:15], off offset:768
	global_load_dwordx4 v[90:93], v[10:11], off offset:832
	global_load_dwordx4 v[94:97], v[14:15], off offset:832
	global_load_dwordx4 v[98:101], v[10:11], off offset:896
	global_load_dwordx4 v[102:105], v[14:15], off offset:896
	global_load_dwordx4 v[106:109], v[10:11], off offset:960
	global_load_dwordx4 v[110:113], v[14:15], off offset:960
	s_waitcnt vmcnt(14) lgkmcnt(7)
	v_mfma_f32_16x16x32_bf16 v[6:9], v[18:21], v[34:37], v[6:9]
	v_mfma_f32_16x16x32_bf16 v[2:5], v[18:21], v[38:41], v[2:5]
	s_waitcnt vmcnt(12) lgkmcnt(6)
	v_mfma_f32_16x16x32_bf16 v[6:9], v[22:25], v[42:45], v[6:9]
	v_mfma_f32_16x16x32_bf16 v[2:5], v[22:25], v[46:49], v[2:5]
	s_waitcnt vmcnt(10) lgkmcnt(5)
	v_mfma_f32_16x16x32_bf16 v[6:9], v[26:29], v[50:53], v[6:9]
	v_mfma_f32_16x16x32_bf16 v[2:5], v[26:29], v[54:57], v[2:5]
	s_waitcnt vmcnt(8) lgkmcnt(4)
	v_mfma_f32_16x16x32_bf16 v[6:9], v[30:33], v[58:61], v[6:9]
	v_mfma_f32_16x16x32_bf16 v[2:5], v[30:33], v[62:65], v[2:5]
	ds_read_b128 v[18:21], v114 offset:1024
	ds_read_b128 v[22:25], v115 offset:1024
	ds_read_b128 v[26:29], v114 offset:1152
	ds_read_b128 v[30:33], v115 offset:1152
	global_load_dwordx4 v[34:37], v[10:11], off offset:1024
	global_load_dwordx4 v[38:41], v[14:15], off offset:1024
	global_load_dwordx4 v[42:45], v[10:11], off offset:1088
	global_load_dwordx4 v[46:49], v[14:15], off offset:1088
	global_load_dwordx4 v[50:53], v[10:11], off offset:1152
	global_load_dwordx4 v[54:57], v[14:15], off offset:1152
	global_load_dwordx4 v[58:61], v[10:11], off offset:1216
	global_load_dwordx4 v[62:65], v[14:15], off offset:1216
	s_waitcnt vmcnt(14) lgkmcnt(7)
	v_mfma_f32_16x16x32_bf16 v[6:9], v[66:69], v[82:85], v[6:9]
	v_mfma_f32_16x16x32_bf16 v[2:5], v[66:69], v[86:89], v[2:5]
	s_waitcnt vmcnt(12) lgkmcnt(6)
	v_mfma_f32_16x16x32_bf16 v[6:9], v[70:73], v[90:93], v[6:9]
	v_mfma_f32_16x16x32_bf16 v[2:5], v[70:73], v[94:97], v[2:5]
	s_waitcnt vmcnt(10) lgkmcnt(5)
	v_mfma_f32_16x16x32_bf16 v[6:9], v[74:77], v[98:101], v[6:9]
	v_mfma_f32_16x16x32_bf16 v[2:5], v[74:77], v[102:105], v[2:5]
	s_waitcnt vmcnt(8) lgkmcnt(4)
	v_mfma_f32_16x16x32_bf16 v[6:9], v[78:81], v[106:109], v[6:9]
	v_mfma_f32_16x16x32_bf16 v[2:5], v[78:81], v[110:113], v[2:5]
	ds_read_b128 v[66:69], v114 offset:1280
	ds_read_b128 v[70:73], v115 offset:1280
	ds_read_b128 v[74:77], v114 offset:1408
	ds_read_b128 v[78:81], v115 offset:1408
	global_load_dwordx4 v[82:85], v[10:11], off offset:1280
	global_load_dwordx4 v[86:89], v[14:15], off offset:1280
	global_load_dwordx4 v[90:93], v[10:11], off offset:1344
	global_load_dwordx4 v[94:97], v[14:15], off offset:1344
	global_load_dwordx4 v[98:101], v[10:11], off offset:1408
	global_load_dwordx4 v[102:105], v[14:15], off offset:1408
	global_load_dwordx4 v[106:109], v[10:11], off offset:1472
	global_load_dwordx4 v[110:113], v[14:15], off offset:1472
	s_waitcnt vmcnt(14) lgkmcnt(7)
	v_mfma_f32_16x16x32_bf16 v[6:9], v[18:21], v[34:37], v[6:9]
	v_mfma_f32_16x16x32_bf16 v[2:5], v[18:21], v[38:41], v[2:5]
	s_waitcnt vmcnt(12) lgkmcnt(6)
	v_mfma_f32_16x16x32_bf16 v[6:9], v[22:25], v[42:45], v[6:9]
	v_mfma_f32_16x16x32_bf16 v[2:5], v[22:25], v[46:49], v[2:5]
	s_waitcnt vmcnt(10) lgkmcnt(5)
	v_mfma_f32_16x16x32_bf16 v[6:9], v[26:29], v[50:53], v[6:9]
	v_mfma_f32_16x16x32_bf16 v[2:5], v[26:29], v[54:57], v[2:5]
	s_waitcnt vmcnt(8) lgkmcnt(4)
	v_mfma_f32_16x16x32_bf16 v[6:9], v[30:33], v[58:61], v[6:9]
	v_mfma_f32_16x16x32_bf16 v[2:5], v[30:33], v[62:65], v[2:5]
	ds_read_b128 v[18:21], v114 offset:1536
	ds_read_b128 v[22:25], v115 offset:1536
	ds_read_b128 v[26:29], v114 offset:1664
	ds_read_b128 v[30:33], v115 offset:1664
	global_load_dwordx4 v[34:37], v[10:11], off offset:1536
	global_load_dwordx4 v[38:41], v[14:15], off offset:1536
	global_load_dwordx4 v[42:45], v[10:11], off offset:1600
	global_load_dwordx4 v[46:49], v[14:15], off offset:1600
	global_load_dwordx4 v[50:53], v[10:11], off offset:1664
	global_load_dwordx4 v[54:57], v[14:15], off offset:1664
	global_load_dwordx4 v[58:61], v[10:11], off offset:1728
	global_load_dwordx4 v[62:65], v[14:15], off offset:1728
	s_waitcnt vmcnt(14) lgkmcnt(7)
	v_mfma_f32_16x16x32_bf16 v[6:9], v[66:69], v[82:85], v[6:9]
	v_mfma_f32_16x16x32_bf16 v[2:5], v[66:69], v[86:89], v[2:5]
	s_waitcnt vmcnt(12) lgkmcnt(6)
	v_mfma_f32_16x16x32_bf16 v[6:9], v[70:73], v[90:93], v[6:9]
	v_mfma_f32_16x16x32_bf16 v[2:5], v[70:73], v[94:97], v[2:5]
	s_waitcnt vmcnt(10) lgkmcnt(5)
	v_mfma_f32_16x16x32_bf16 v[6:9], v[74:77], v[98:101], v[6:9]
	v_mfma_f32_16x16x32_bf16 v[2:5], v[74:77], v[102:105], v[2:5]
	s_waitcnt vmcnt(8) lgkmcnt(4)
	v_mfma_f32_16x16x32_bf16 v[6:9], v[78:81], v[106:109], v[6:9]
	v_mfma_f32_16x16x32_bf16 v[2:5], v[78:81], v[110:113], v[2:5]
	ds_read_b128 v[66:69], v114 offset:1792
	ds_read_b128 v[70:73], v115 offset:1792
	ds_read_b128 v[74:77], v114 offset:1920
	ds_read_b128 v[78:81], v115 offset:1920
	global_load_dwordx4 v[82:85], v[10:11], off offset:1792
	global_load_dwordx4 v[86:89], v[14:15], off offset:1792
	global_load_dwordx4 v[90:93], v[10:11], off offset:1856
	global_load_dwordx4 v[94:97], v[14:15], off offset:1856
	global_load_dwordx4 v[98:101], v[10:11], off offset:1920
	global_load_dwordx4 v[102:105], v[14:15], off offset:1920
	global_load_dwordx4 v[106:109], v[10:11], off offset:1984
	global_load_dwordx4 v[110:113], v[14:15], off offset:1984
	s_waitcnt vmcnt(14) lgkmcnt(7)
	v_mfma_f32_16x16x32_bf16 v[6:9], v[18:21], v[34:37], v[6:9]
	v_mfma_f32_16x16x32_bf16 v[2:5], v[18:21], v[38:41], v[2:5]
	s_waitcnt vmcnt(12) lgkmcnt(6)
	v_mfma_f32_16x16x32_bf16 v[6:9], v[22:25], v[42:45], v[6:9]
	v_mfma_f32_16x16x32_bf16 v[2:5], v[22:25], v[46:49], v[2:5]
	s_waitcnt vmcnt(10) lgkmcnt(5)
	v_mfma_f32_16x16x32_bf16 v[6:9], v[26:29], v[50:53], v[6:9]
	v_mfma_f32_16x16x32_bf16 v[2:5], v[26:29], v[54:57], v[2:5]
	s_waitcnt vmcnt(8) lgkmcnt(4)
	v_mfma_f32_16x16x32_bf16 v[6:9], v[30:33], v[58:61], v[6:9]
	v_mfma_f32_16x16x32_bf16 v[2:5], v[30:33], v[62:65], v[2:5]
	ds_read_b128 v[18:21], v116 offset:2048
	ds_read_b128 v[22:25], v117 offset:2048
	ds_read_b128 v[26:29], v116 offset:2176
	ds_read_b128 v[30:33], v117 offset:2176
	global_load_dwordx4 v[34:37], v[10:11], off offset:2048
	global_load_dwordx4 v[38:41], v[14:15], off offset:2048
	global_load_dwordx4 v[42:45], v[10:11], off offset:2112
	global_load_dwordx4 v[46:49], v[14:15], off offset:2112
	global_load_dwordx4 v[50:53], v[10:11], off offset:2176
	global_load_dwordx4 v[54:57], v[14:15], off offset:2176
	global_load_dwordx4 v[58:61], v[10:11], off offset:2240
	global_load_dwordx4 v[62:65], v[14:15], off offset:2240
	s_waitcnt vmcnt(14) lgkmcnt(7)
	v_mfma_f32_16x16x32_bf16 v[6:9], v[66:69], v[82:85], v[6:9]
	v_mfma_f32_16x16x32_bf16 v[2:5], v[66:69], v[86:89], v[2:5]
	s_waitcnt vmcnt(12) lgkmcnt(6)
	v_mfma_f32_16x16x32_bf16 v[6:9], v[70:73], v[90:93], v[6:9]
	v_mfma_f32_16x16x32_bf16 v[2:5], v[70:73], v[94:97], v[2:5]
	s_waitcnt vmcnt(10) lgkmcnt(5)
	v_mfma_f32_16x16x32_bf16 v[6:9], v[74:77], v[98:101], v[6:9]
	v_mfma_f32_16x16x32_bf16 v[2:5], v[74:77], v[102:105], v[2:5]
	s_waitcnt vmcnt(8) lgkmcnt(4)
	v_mfma_f32_16x16x32_bf16 v[6:9], v[78:81], v[106:109], v[6:9]
	v_mfma_f32_16x16x32_bf16 v[2:5], v[78:81], v[110:113], v[2:5]
	ds_read_b128 v[66:69], v116 offset:2304
	ds_read_b128 v[70:73], v117 offset:2304
	ds_read_b128 v[74:77], v116 offset:2432
	ds_read_b128 v[78:81], v117 offset:2432
	global_load_dwordx4 v[82:85], v[10:11], off offset:2304
	global_load_dwordx4 v[86:89], v[14:15], off offset:2304
	global_load_dwordx4 v[90:93], v[10:11], off offset:2368
	global_load_dwordx4 v[94:97], v[14:15], off offset:2368
	global_load_dwordx4 v[98:101], v[10:11], off offset:2432
	global_load_dwordx4 v[102:105], v[14:15], off offset:2432
	global_load_dwordx4 v[106:109], v[10:11], off offset:2496
	global_load_dwordx4 v[110:113], v[14:15], off offset:2496
	s_waitcnt vmcnt(14) lgkmcnt(7)
	v_mfma_f32_16x16x32_bf16 v[6:9], v[18:21], v[34:37], v[6:9]
	v_mfma_f32_16x16x32_bf16 v[2:5], v[18:21], v[38:41], v[2:5]
	s_waitcnt vmcnt(12) lgkmcnt(6)
	v_mfma_f32_16x16x32_bf16 v[6:9], v[22:25], v[42:45], v[6:9]
	v_mfma_f32_16x16x32_bf16 v[2:5], v[22:25], v[46:49], v[2:5]
	s_waitcnt vmcnt(10) lgkmcnt(5)
	v_mfma_f32_16x16x32_bf16 v[6:9], v[26:29], v[50:53], v[6:9]
	v_mfma_f32_16x16x32_bf16 v[2:5], v[26:29], v[54:57], v[2:5]
	s_waitcnt vmcnt(8) lgkmcnt(4)
	v_mfma_f32_16x16x32_bf16 v[6:9], v[30:33], v[58:61], v[6:9]
	v_mfma_f32_16x16x32_bf16 v[2:5], v[30:33], v[62:65], v[2:5]
	ds_read_b128 v[18:21], v116 offset:2560
	ds_read_b128 v[22:25], v117 offset:2560
	ds_read_b128 v[26:29], v116 offset:2688
	ds_read_b128 v[30:33], v117 offset:2688
	global_load_dwordx4 v[34:37], v[10:11], off offset:2560
	global_load_dwordx4 v[38:41], v[14:15], off offset:2560
	global_load_dwordx4 v[42:45], v[10:11], off offset:2624
	global_load_dwordx4 v[46:49], v[14:15], off offset:2624
	global_load_dwordx4 v[50:53], v[10:11], off offset:2688
	global_load_dwordx4 v[54:57], v[14:15], off offset:2688
	global_load_dwordx4 v[58:61], v[10:11], off offset:2752
	global_load_dwordx4 v[62:65], v[14:15], off offset:2752
	s_waitcnt vmcnt(14) lgkmcnt(7)
	v_mfma_f32_16x16x32_bf16 v[6:9], v[66:69], v[82:85], v[6:9]
	v_mfma_f32_16x16x32_bf16 v[2:5], v[66:69], v[86:89], v[2:5]
	s_waitcnt vmcnt(12) lgkmcnt(6)
	v_mfma_f32_16x16x32_bf16 v[6:9], v[70:73], v[90:93], v[6:9]
	v_mfma_f32_16x16x32_bf16 v[2:5], v[70:73], v[94:97], v[2:5]
	s_waitcnt vmcnt(10) lgkmcnt(5)
	v_mfma_f32_16x16x32_bf16 v[6:9], v[74:77], v[98:101], v[6:9]
	v_mfma_f32_16x16x32_bf16 v[2:5], v[74:77], v[102:105], v[2:5]
	s_waitcnt vmcnt(8) lgkmcnt(4)
	v_mfma_f32_16x16x32_bf16 v[6:9], v[78:81], v[106:109], v[6:9]
	v_mfma_f32_16x16x32_bf16 v[2:5], v[78:81], v[110:113], v[2:5]
	ds_read_b128 v[66:69], v116 offset:2816
	ds_read_b128 v[70:73], v117 offset:2816
	ds_read_b128 v[74:77], v116 offset:2944
	ds_read_b128 v[78:81], v117 offset:2944
	global_load_dwordx4 v[82:85], v[10:11], off offset:2816
	global_load_dwordx4 v[86:89], v[14:15], off offset:2816
	global_load_dwordx4 v[90:93], v[10:11], off offset:2880
	global_load_dwordx4 v[94:97], v[14:15], off offset:2880
	global_load_dwordx4 v[98:101], v[10:11], off offset:2944
	global_load_dwordx4 v[102:105], v[14:15], off offset:2944
	global_load_dwordx4 v[106:109], v[10:11], off offset:3008
	global_load_dwordx4 v[110:113], v[14:15], off offset:3008
	s_waitcnt vmcnt(14) lgkmcnt(7)
	v_mfma_f32_16x16x32_bf16 v[6:9], v[18:21], v[34:37], v[6:9]
	v_mfma_f32_16x16x32_bf16 v[2:5], v[18:21], v[38:41], v[2:5]
	s_waitcnt vmcnt(12) lgkmcnt(6)
	v_mfma_f32_16x16x32_bf16 v[6:9], v[22:25], v[42:45], v[6:9]
	v_mfma_f32_16x16x32_bf16 v[2:5], v[22:25], v[46:49], v[2:5]
	s_waitcnt vmcnt(10) lgkmcnt(5)
	v_mfma_f32_16x16x32_bf16 v[6:9], v[26:29], v[50:53], v[6:9]
	v_mfma_f32_16x16x32_bf16 v[2:5], v[26:29], v[54:57], v[2:5]
	s_waitcnt vmcnt(8) lgkmcnt(4)
	v_mfma_f32_16x16x32_bf16 v[6:9], v[30:33], v[58:61], v[6:9]
	v_mfma_f32_16x16x32_bf16 v[2:5], v[30:33], v[62:65], v[2:5]
	ds_read_b128 v[18:21], v116 offset:3072
	ds_read_b128 v[22:25], v117 offset:3072
	ds_read_b128 v[26:29], v116 offset:3200
	ds_read_b128 v[30:33], v117 offset:3200
	global_load_dwordx4 v[34:37], v[10:11], off offset:3072
	global_load_dwordx4 v[38:41], v[14:15], off offset:3072
	global_load_dwordx4 v[42:45], v[10:11], off offset:3136
	global_load_dwordx4 v[46:49], v[14:15], off offset:3136
	global_load_dwordx4 v[50:53], v[10:11], off offset:3200
	global_load_dwordx4 v[54:57], v[14:15], off offset:3200
	global_load_dwordx4 v[58:61], v[10:11], off offset:3264
	global_load_dwordx4 v[62:65], v[14:15], off offset:3264
	s_waitcnt vmcnt(14) lgkmcnt(7)
	v_mfma_f32_16x16x32_bf16 v[6:9], v[66:69], v[82:85], v[6:9]
	v_mfma_f32_16x16x32_bf16 v[2:5], v[66:69], v[86:89], v[2:5]
	s_waitcnt vmcnt(12) lgkmcnt(6)
	v_mfma_f32_16x16x32_bf16 v[6:9], v[70:73], v[90:93], v[6:9]
	v_mfma_f32_16x16x32_bf16 v[2:5], v[70:73], v[94:97], v[2:5]
	s_waitcnt vmcnt(10) lgkmcnt(5)
	v_mfma_f32_16x16x32_bf16 v[6:9], v[74:77], v[98:101], v[6:9]
	v_mfma_f32_16x16x32_bf16 v[2:5], v[74:77], v[102:105], v[2:5]
	s_waitcnt vmcnt(8) lgkmcnt(4)
	v_mfma_f32_16x16x32_bf16 v[6:9], v[78:81], v[106:109], v[6:9]
	v_mfma_f32_16x16x32_bf16 v[2:5], v[78:81], v[110:113], v[2:5]
	ds_read_b128 v[66:69], v116 offset:3328
	ds_read_b128 v[70:73], v117 offset:3328
	ds_read_b128 v[74:77], v116 offset:3456
	ds_read_b128 v[78:81], v117 offset:3456
	global_load_dwordx4 v[82:85], v[10:11], off offset:3328
	global_load_dwordx4 v[86:89], v[14:15], off offset:3328
	global_load_dwordx4 v[90:93], v[10:11], off offset:3392
	global_load_dwordx4 v[94:97], v[14:15], off offset:3392
	global_load_dwordx4 v[98:101], v[10:11], off offset:3456
	global_load_dwordx4 v[102:105], v[14:15], off offset:3456
	global_load_dwordx4 v[106:109], v[10:11], off offset:3520
	global_load_dwordx4 v[110:113], v[14:15], off offset:3520
	s_waitcnt vmcnt(14) lgkmcnt(7)
	v_mfma_f32_16x16x32_bf16 v[6:9], v[18:21], v[34:37], v[6:9]
	v_mfma_f32_16x16x32_bf16 v[2:5], v[18:21], v[38:41], v[2:5]
	s_waitcnt vmcnt(12) lgkmcnt(6)
	v_mfma_f32_16x16x32_bf16 v[6:9], v[22:25], v[42:45], v[6:9]
	v_mfma_f32_16x16x32_bf16 v[2:5], v[22:25], v[46:49], v[2:5]
	s_waitcnt vmcnt(10) lgkmcnt(5)
	v_mfma_f32_16x16x32_bf16 v[6:9], v[26:29], v[50:53], v[6:9]
	v_mfma_f32_16x16x32_bf16 v[2:5], v[26:29], v[54:57], v[2:5]
	s_waitcnt vmcnt(8) lgkmcnt(4)
	v_mfma_f32_16x16x32_bf16 v[6:9], v[30:33], v[58:61], v[6:9]
	v_mfma_f32_16x16x32_bf16 v[2:5], v[30:33], v[62:65], v[2:5]
	ds_read_b128 v[18:21], v116 offset:3584
	ds_read_b128 v[22:25], v117 offset:3584
	ds_read_b128 v[26:29], v116 offset:3712
	ds_read_b128 v[30:33], v117 offset:3712
	global_load_dwordx4 v[34:37], v[10:11], off offset:3584
	global_load_dwordx4 v[38:41], v[14:15], off offset:3584
	global_load_dwordx4 v[42:45], v[10:11], off offset:3648
	global_load_dwordx4 v[46:49], v[14:15], off offset:3648
	global_load_dwordx4 v[50:53], v[10:11], off offset:3712
	global_load_dwordx4 v[54:57], v[14:15], off offset:3712
	global_load_dwordx4 v[58:61], v[10:11], off offset:3776
	global_load_dwordx4 v[62:65], v[14:15], off offset:3776
	s_waitcnt vmcnt(14) lgkmcnt(7)
	v_mfma_f32_16x16x32_bf16 v[6:9], v[66:69], v[82:85], v[6:9]
	v_mfma_f32_16x16x32_bf16 v[2:5], v[66:69], v[86:89], v[2:5]
	s_waitcnt vmcnt(12) lgkmcnt(6)
	v_mfma_f32_16x16x32_bf16 v[6:9], v[70:73], v[90:93], v[6:9]
	v_mfma_f32_16x16x32_bf16 v[2:5], v[70:73], v[94:97], v[2:5]
	s_waitcnt vmcnt(10) lgkmcnt(5)
	v_mfma_f32_16x16x32_bf16 v[6:9], v[74:77], v[98:101], v[6:9]
	v_mfma_f32_16x16x32_bf16 v[2:5], v[74:77], v[102:105], v[2:5]
	s_waitcnt vmcnt(8) lgkmcnt(4)
	v_mfma_f32_16x16x32_bf16 v[6:9], v[78:81], v[106:109], v[6:9]
	v_mfma_f32_16x16x32_bf16 v[2:5], v[78:81], v[110:113], v[2:5]
	ds_read_b128 v[66:69], v116 offset:3840
	ds_read_b128 v[70:73], v117 offset:3840
	ds_read_b128 v[74:77], v116 offset:3968
	ds_read_b128 v[78:81], v117 offset:3968
	global_load_dwordx4 v[82:85], v[10:11], off offset:3840
	global_load_dwordx4 v[86:89], v[14:15], off offset:3840
	global_load_dwordx4 v[90:93], v[10:11], off offset:3904
	global_load_dwordx4 v[94:97], v[14:15], off offset:3904
	global_load_dwordx4 v[98:101], v[10:11], off offset:3968
	global_load_dwordx4 v[102:105], v[14:15], off offset:3968
	global_load_dwordx4 v[106:109], v[10:11], off offset:4032
	global_load_dwordx4 v[110:113], v[14:15], off offset:4032
	s_waitcnt vmcnt(14) lgkmcnt(7)
	v_mfma_f32_16x16x32_bf16 v[6:9], v[18:21], v[34:37], v[6:9]
	v_mfma_f32_16x16x32_bf16 v[2:5], v[18:21], v[38:41], v[2:5]
	s_waitcnt vmcnt(12) lgkmcnt(6)
	v_mfma_f32_16x16x32_bf16 v[6:9], v[22:25], v[42:45], v[6:9]
	v_mfma_f32_16x16x32_bf16 v[2:5], v[22:25], v[46:49], v[2:5]
	s_waitcnt vmcnt(10) lgkmcnt(5)
	v_mfma_f32_16x16x32_bf16 v[6:9], v[26:29], v[50:53], v[6:9]
	v_mfma_f32_16x16x32_bf16 v[2:5], v[26:29], v[54:57], v[2:5]
	s_waitcnt vmcnt(8) lgkmcnt(4)
	v_mfma_f32_16x16x32_bf16 v[6:9], v[30:33], v[58:61], v[6:9]
	v_mfma_f32_16x16x32_bf16 v[2:5], v[30:33], v[62:65], v[2:5]
	s_waitcnt vmcnt(6) lgkmcnt(3)
	v_mfma_f32_16x16x32_bf16 v[6:9], v[66:69], v[82:85], v[6:9]
	v_mfma_f32_16x16x32_bf16 v[2:5], v[66:69], v[86:89], v[2:5]
	s_waitcnt vmcnt(4) lgkmcnt(2)
	v_mfma_f32_16x16x32_bf16 v[6:9], v[70:73], v[90:93], v[6:9]
	v_mfma_f32_16x16x32_bf16 v[2:5], v[70:73], v[94:97], v[2:5]
	s_waitcnt vmcnt(2) lgkmcnt(1)
	v_mfma_f32_16x16x32_bf16 v[6:9], v[74:77], v[98:101], v[6:9]
	v_mfma_f32_16x16x32_bf16 v[2:5], v[74:77], v[102:105], v[2:5]
	s_waitcnt vmcnt(0) lgkmcnt(0)
	v_mfma_f32_16x16x32_bf16 v[6:9], v[78:81], v[106:109], v[6:9]
	v_mfma_f32_16x16x32_bf16 v[2:5], v[78:81], v[110:113], v[2:5]
	s_lshl_b32 s14, s81, 6
	s_and_b32 s18, s14, 0xffffe000
	s_ashr_i32 s19, s18, 31
	v_lshl_add_u64 v[66:67], s[18:19], 2, v[142:143]
	s_mov_b64 s[18:19], 0x1000
	v_lshl_add_u64 v[68:69], v[66:67], 0, s[18:19]
	s_mov_b64 s[18:19], 0x2000
	v_lshl_add_u64 v[70:71], v[66:67], 0, s[18:19]
	s_mov_b64 s[18:19], 0x3000
	v_lshl_add_u64 v[72:73], v[66:67], 0, s[18:19]
	s_mov_b64 s[18:19], 0x4000
	v_lshl_add_u64 v[74:75], v[66:67], 0, s[18:19]
	s_mov_b64 s[18:19], 0x5000
	v_lshl_add_u64 v[76:77], v[66:67], 0, s[18:19]
	s_mov_b64 s[18:19], 0x6000
	v_lshl_add_u64 v[78:79], v[66:67], 0, s[18:19]
	s_mov_b64 s[18:19], 0x7000
	v_lshl_add_u64 v[80:81], v[66:67], 0, s[18:19]
	global_load_dword v30, v[66:67], off
	global_load_dword v31, v[66:67], off offset:1024
	global_load_dword v32, v[66:67], off offset:2048
	global_load_dword v33, v[66:67], off offset:3072
	global_load_dword v34, v[68:69], off
	global_load_dword v35, v[68:69], off offset:1024
	global_load_dword v36, v[68:69], off offset:2048
	global_load_dword v37, v[68:69], off offset:3072
	global_load_dword v38, v[70:71], off
	global_load_dword v39, v[70:71], off offset:1024
	global_load_dword v40, v[70:71], off offset:2048
	global_load_dword v41, v[70:71], off offset:3072
	global_load_dword v42, v[72:73], off
	global_load_dword v43, v[72:73], off offset:1024
	global_load_dword v44, v[72:73], off offset:2048
	global_load_dword v45, v[72:73], off offset:3072
	global_load_dword v46, v[74:75], off
	global_load_dword v47, v[74:75], off offset:1024
	global_load_dword v48, v[74:75], off offset:2048
	global_load_dword v49, v[74:75], off offset:3072
	global_load_dword v50, v[76:77], off
	global_load_dword v51, v[76:77], off offset:1024
	global_load_dword v52, v[76:77], off offset:2048
	global_load_dword v53, v[76:77], off offset:3072
	global_load_dword v54, v[78:79], off
	global_load_dword v55, v[78:79], off offset:1024
	global_load_dword v56, v[78:79], off offset:2048
	global_load_dword v57, v[78:79], off offset:3072
	global_load_dword v58, v[80:81], off
	global_load_dword v59, v[80:81], off offset:1024
	global_load_dword v60, v[80:81], off offset:2048
	global_load_dword v61, v[80:81], off offset:3072
	global_load_dword v82, v[66:67], off offset:64
	global_load_dword v83, v[66:67], off offset:1088
	global_load_dword v84, v[66:67], off offset:2112
	global_load_dword v85, v[66:67], off offset:3136
	global_load_dword v86, v[68:69], off offset:64
	global_load_dword v87, v[68:69], off offset:1088
	global_load_dword v88, v[68:69], off offset:2112
	global_load_dword v89, v[68:69], off offset:3136
	global_load_dword v90, v[70:71], off offset:64
	global_load_dword v91, v[70:71], off offset:1088
	global_load_dword v92, v[70:71], off offset:2112
	global_load_dword v93, v[70:71], off offset:3136
	global_load_dword v94, v[72:73], off offset:64
	global_load_dword v95, v[72:73], off offset:1088
	global_load_dword v96, v[72:73], off offset:2112
	global_load_dword v97, v[72:73], off offset:3136
	s_waitcnt vmcnt(47)
	v_add_f32_e32 v0, 0, v30
	s_waitcnt vmcnt(46)
	v_add_f32_e32 v0, v0, v31
	s_waitcnt vmcnt(45)
	v_add_f32_e32 v0, v0, v32
	s_waitcnt vmcnt(44)
	v_add_f32_e32 v0, v0, v33
	s_waitcnt vmcnt(43)
	v_add_f32_e32 v0, v0, v34
	s_waitcnt vmcnt(42)
	v_add_f32_e32 v0, v0, v35
	s_waitcnt vmcnt(41)
	v_add_f32_e32 v0, v0, v36
	s_waitcnt vmcnt(40)
	v_add_f32_e32 v0, v0, v37
	s_waitcnt vmcnt(39)
	v_add_f32_e32 v0, v0, v38
	s_waitcnt vmcnt(38)
	v_add_f32_e32 v0, v0, v39
	s_waitcnt vmcnt(37)
	v_add_f32_e32 v0, v0, v40
	s_waitcnt vmcnt(36)
	v_add_f32_e32 v0, v0, v41
	s_waitcnt vmcnt(35)
	v_add_f32_e32 v0, v0, v42
	s_waitcnt vmcnt(34)
	v_add_f32_e32 v0, v0, v43
	s_waitcnt vmcnt(33)
	v_add_f32_e32 v0, v0, v44
	s_waitcnt vmcnt(32)
	v_add_f32_e32 v0, v0, v45
	s_waitcnt vmcnt(31)
	v_add_f32_e32 v0, v0, v46
	s_waitcnt vmcnt(30)
	v_add_f32_e32 v0, v0, v47
	s_waitcnt vmcnt(29)
	v_add_f32_e32 v0, v0, v48
	s_waitcnt vmcnt(28)
	v_add_f32_e32 v0, v0, v49
	s_waitcnt vmcnt(27)
	v_add_f32_e32 v0, v0, v50
	s_waitcnt vmcnt(26)
	v_add_f32_e32 v0, v0, v51
	s_waitcnt vmcnt(25)
	v_add_f32_e32 v0, v0, v52
	s_waitcnt vmcnt(24)
	v_add_f32_e32 v0, v0, v53
	s_waitcnt vmcnt(23)
	v_add_f32_e32 v0, v0, v54
	s_waitcnt vmcnt(22)
	v_add_f32_e32 v0, v0, v55
	s_waitcnt vmcnt(21)
	v_add_f32_e32 v0, v0, v56
	s_waitcnt vmcnt(20)
	v_add_f32_e32 v0, v0, v57
	s_waitcnt vmcnt(19)
	v_add_f32_e32 v0, v0, v58
	s_waitcnt vmcnt(18)
	v_add_f32_e32 v0, v0, v59
	s_waitcnt vmcnt(17)
	v_add_f32_e32 v0, v0, v60
	s_waitcnt vmcnt(16)
	v_add_f32_e32 v0, v0, v61
	global_load_dword v98, v[74:75], off offset:64
	global_load_dword v99, v[74:75], off offset:1088
	global_load_dword v100, v[74:75], off offset:2112
	global_load_dword v101, v[74:75], off offset:3136
	global_load_dword v102, v[76:77], off offset:64
	global_load_dword v103, v[76:77], off offset:1088
	global_load_dword v104, v[76:77], off offset:2112
	global_load_dword v105, v[76:77], off offset:3136
	global_load_dword v106, v[78:79], off offset:64
	global_load_dword v107, v[78:79], off offset:1088
	global_load_dword v108, v[78:79], off offset:2112
	global_load_dword v109, v[78:79], off offset:3136
	global_load_dword v110, v[80:81], off offset:64
	global_load_dword v111, v[80:81], off offset:1088
	global_load_dword v112, v[80:81], off offset:2112
	global_load_dword v113, v[80:81], off offset:3136
	v_add_f32_e32 v6, v6, v0
	v_mul_f32_e32 v26, 0x3d372713, v6
	v_mul_f32_e32 v26, v6, v26
	v_fma_f32 v26, v6, v26, v6
	v_mul_f32_e32 v26, 0x3f4c422a, v26
	v_add_f32_e32 v26, v26, v26
	v_mul_f32_e32 v26, 0x3fb8aa3b, v26
	v_exp_f32_e32 v26, v26
	v_mul_f32_e32 v6, 0.5, v6
	v_add_f32_e32 v26, 1.0, v26
	v_div_scale_f32 v27, s[18:19], v26, v26, 2.0
	v_rcp_f32_e32 v28, v27
	s_nop 0
	v_fma_f32 v29, -v27, v28, 1.0
	v_fmac_f32_e32 v28, v29, v28
	v_div_scale_f32 v29, vcc, 2.0, v26, 2.0
	v_mul_f32_e32 v30, v29, v28
	v_fma_f32 v31, -v27, v30, v29
	v_fmac_f32_e32 v30, v31, v28
	v_fma_f32 v27, -v27, v30, v29
	v_div_fmas_f32 v27, v27, v28, v30
	v_div_fixup_f32 v26, v27, v26, 2.0
	v_sub_f32_e32 v26, 1.0, v26
	v_add_f32_e32 v26, 1.0, v26
	v_mul_f32_e32 v6, v6, v26
	v_cvt_pk_bf16_f32 v6, v6, s0
	ds_write_b16 v231, v6 offset:36864
	v_add_f32_e32 v6, v7, v0
	v_mul_f32_e32 v7, 0x3d372713, v6
	v_mul_f32_e32 v7, v6, v7
	v_fma_f32 v7, v6, v7, v6
	v_mul_f32_e32 v7, 0x3f4c422a, v7
	v_add_f32_e32 v7, v7, v7
	v_mul_f32_e32 v7, 0x3fb8aa3b, v7
	v_exp_f32_e32 v7, v7
	v_mul_f32_e32 v6, 0.5, v6
	v_add_f32_e32 v7, 1.0, v7
	v_div_scale_f32 v26, s[18:19], v7, v7, 2.0
	v_rcp_f32_e32 v27, v26
	s_nop 0
	v_fma_f32 v28, -v26, v27, 1.0
	v_fmac_f32_e32 v27, v28, v27
	v_div_scale_f32 v28, vcc, 2.0, v7, 2.0
	v_mul_f32_e32 v29, v28, v27
	v_fma_f32 v30, -v26, v29, v28
	v_fmac_f32_e32 v29, v30, v27
	v_fma_f32 v26, -v26, v29, v28
	v_div_fmas_f32 v26, v26, v27, v29
	v_div_fixup_f32 v7, v26, v7, 2.0
	v_sub_f32_e32 v7, 1.0, v7
	v_add_f32_e32 v7, 1.0, v7
	v_mul_f32_e32 v6, v6, v7
	v_cvt_pk_bf16_f32 v6, v6, s0
	ds_write_b16 v231, v6 offset:37392
	v_add_f32_e32 v6, v8, v0
	v_mul_f32_e32 v7, 0x3d372713, v6
	v_mul_f32_e32 v7, v6, v7
	v_fma_f32 v7, v6, v7, v6
	v_mul_f32_e32 v7, 0x3f4c422a, v7
	v_add_f32_e32 v7, v7, v7
	v_mul_f32_e32 v7, 0x3fb8aa3b, v7
	v_exp_f32_e32 v7, v7
	v_mul_f32_e32 v6, 0.5, v6
	v_add_f32_e32 v0, v9, v0
	v_add_f32_e32 v7, 1.0, v7
	v_div_scale_f32 v8, s[18:19], v7, v7, 2.0
	v_rcp_f32_e32 v26, v8
	s_nop 0
	v_fma_f32 v27, -v8, v26, 1.0
	v_fmac_f32_e32 v26, v27, v26
	v_div_scale_f32 v27, vcc, 2.0, v7, 2.0
	v_mul_f32_e32 v28, v27, v26
	v_fma_f32 v29, -v8, v28, v27
	v_fmac_f32_e32 v28, v29, v26
	v_fma_f32 v8, -v8, v28, v27
	v_div_fmas_f32 v8, v8, v26, v28
	v_div_fixup_f32 v7, v8, v7, 2.0
	v_sub_f32_e32 v7, 1.0, v7
	v_add_f32_e32 v7, 1.0, v7
	v_mul_f32_e32 v6, v6, v7
	v_cvt_pk_bf16_f32 v6, v6, s0
	ds_write_b16 v231, v6 offset:37920
	v_mul_f32_e32 v6, 0x3d372713, v0
	v_mul_f32_e32 v6, v0, v6
	v_fma_f32 v6, v0, v6, v0
	v_mul_f32_e32 v6, 0x3f4c422a, v6
	v_add_f32_e32 v6, v6, v6
	v_mul_f32_e32 v6, 0x3fb8aa3b, v6
	v_exp_f32_e32 v6, v6
	v_mul_f32_e32 v0, 0.5, v0
	v_add_f32_e32 v6, 1.0, v6
	v_div_scale_f32 v7, s[18:19], v6, v6, 2.0
	v_rcp_f32_e32 v8, v7
	s_nop 0
	v_fma_f32 v9, -v7, v8, 1.0
	v_fmac_f32_e32 v8, v9, v8
	v_div_scale_f32 v9, vcc, 2.0, v6, 2.0
	v_mul_f32_e32 v26, v9, v8
	v_fma_f32 v27, -v7, v26, v9
	v_fmac_f32_e32 v26, v27, v8
	v_fma_f32 v7, -v7, v26, v9
	v_div_fmas_f32 v7, v7, v8, v26
	v_div_fixup_f32 v6, v7, v6, 2.0
	v_sub_f32_e32 v6, 1.0, v6
	v_add_f32_e32 v6, 1.0, v6
	v_mul_f32_e32 v0, v0, v6
	v_cvt_pk_bf16_f32 v0, v0, s0
	ds_write_b16 v231, v0 offset:38448
	s_waitcnt vmcnt(31)
	v_add_f32_e32 v0, 0, v82
	s_waitcnt vmcnt(30)
	v_add_f32_e32 v0, v0, v83
	s_waitcnt vmcnt(29)
	v_add_f32_e32 v0, v0, v84
	s_waitcnt vmcnt(28)
	v_add_f32_e32 v0, v0, v85
	s_waitcnt vmcnt(27)
	v_add_f32_e32 v0, v0, v86
	s_waitcnt vmcnt(26)
	v_add_f32_e32 v0, v0, v87
	s_waitcnt vmcnt(25)
	v_add_f32_e32 v0, v0, v88
	s_waitcnt vmcnt(24)
	v_add_f32_e32 v0, v0, v89
	s_waitcnt vmcnt(23)
	v_add_f32_e32 v0, v0, v90
	s_waitcnt vmcnt(22)
	v_add_f32_e32 v0, v0, v91
	s_waitcnt vmcnt(21)
	v_add_f32_e32 v0, v0, v92
	s_waitcnt vmcnt(20)
	v_add_f32_e32 v0, v0, v93
	s_waitcnt vmcnt(19)
	v_add_f32_e32 v0, v0, v94
	s_waitcnt vmcnt(18)
	v_add_f32_e32 v0, v0, v95
	s_waitcnt vmcnt(17)
	v_add_f32_e32 v0, v0, v96
	s_waitcnt vmcnt(16)
	v_add_f32_e32 v0, v0, v97
	s_waitcnt vmcnt(15)
	v_add_f32_e32 v0, v0, v98
	s_waitcnt vmcnt(14)
	v_add_f32_e32 v0, v0, v99
	s_waitcnt vmcnt(13)
	v_add_f32_e32 v0, v0, v100
	s_waitcnt vmcnt(12)
	v_add_f32_e32 v0, v0, v101
	s_waitcnt vmcnt(11)
	v_add_f32_e32 v0, v0, v102
	s_waitcnt vmcnt(10)
	v_add_f32_e32 v0, v0, v103
	s_waitcnt vmcnt(9)
	v_add_f32_e32 v0, v0, v104
	s_waitcnt vmcnt(8)
	v_add_f32_e32 v0, v0, v105
	s_waitcnt vmcnt(7)
	v_add_f32_e32 v0, v0, v106
	s_waitcnt vmcnt(6)
	v_add_f32_e32 v0, v0, v107
	s_waitcnt vmcnt(5)
	v_add_f32_e32 v0, v0, v108
	s_waitcnt vmcnt(4)
	v_add_f32_e32 v0, v0, v109
	s_waitcnt vmcnt(3)
	v_add_f32_e32 v0, v0, v110
	s_waitcnt vmcnt(2)
	v_add_f32_e32 v0, v0, v111
	s_waitcnt vmcnt(1)
	v_add_f32_e32 v0, v0, v112
	s_waitcnt vmcnt(0)
	v_add_f32_e32 v0, v0, v113
	v_add_f32_e32 v2, v2, v0
	v_mul_f32_e32 v6, 0x3d372713, v2
	v_mul_f32_e32 v6, v2, v6
	v_fma_f32 v6, v2, v6, v2
	v_mul_f32_e32 v6, 0x3f4c422a, v6
	v_add_f32_e32 v6, v6, v6
	v_mul_f32_e32 v6, 0x3fb8aa3b, v6
	v_exp_f32_e32 v6, v6
	v_mul_f32_e32 v2, 0.5, v2
	v_add_f32_e32 v6, 1.0, v6
	v_div_scale_f32 v7, s[18:19], v6, v6, 2.0
	v_rcp_f32_e32 v8, v7
	s_nop 0
	v_fma_f32 v9, -v7, v8, 1.0
	v_fmac_f32_e32 v8, v9, v8
	v_div_scale_f32 v9, vcc, 2.0, v6, 2.0
	v_mul_f32_e32 v10, v9, v8
	v_fma_f32 v11, -v7, v10, v9
	v_fmac_f32_e32 v10, v11, v8
	v_fma_f32 v7, -v7, v10, v9
	v_div_fmas_f32 v7, v7, v8, v10
	v_div_fixup_f32 v6, v7, v6, 2.0
	v_sub_f32_e32 v6, 1.0, v6
	v_add_f32_e32 v6, 1.0, v6
	v_mul_f32_e32 v2, v2, v6
	v_cvt_pk_bf16_f32 v2, v2, s0
	ds_write_b16 v231, v2 offset:36896
	v_add_f32_e32 v2, v3, v0
	v_mul_f32_e32 v3, 0x3d372713, v2
	v_mul_f32_e32 v3, v2, v3
	v_fma_f32 v3, v2, v3, v2
	v_mul_f32_e32 v3, 0x3f4c422a, v3
	v_add_f32_e32 v3, v3, v3
	v_mul_f32_e32 v3, 0x3fb8aa3b, v3
	v_exp_f32_e32 v3, v3
	v_mul_f32_e32 v2, 0.5, v2
	v_add_f32_e32 v3, 1.0, v3
	v_div_scale_f32 v6, s[18:19], v3, v3, 2.0
	v_rcp_f32_e32 v7, v6
	s_nop 0
	v_fma_f32 v8, -v6, v7, 1.0
	v_fmac_f32_e32 v7, v8, v7
	v_div_scale_f32 v8, vcc, 2.0, v3, 2.0
	v_mul_f32_e32 v9, v8, v7
	v_fma_f32 v10, -v6, v9, v8
	v_fmac_f32_e32 v9, v10, v7
	v_fma_f32 v6, -v6, v9, v8
	v_div_fmas_f32 v6, v6, v7, v9
	v_div_fixup_f32 v3, v6, v3, 2.0
	v_sub_f32_e32 v3, 1.0, v3
	v_add_f32_e32 v3, 1.0, v3
	v_mul_f32_e32 v2, v2, v3
	v_cvt_pk_bf16_f32 v2, v2, s0
	ds_write_b16 v231, v2 offset:37424
	v_add_f32_e32 v2, v4, v0
	v_mul_f32_e32 v3, 0x3d372713, v2
	v_mul_f32_e32 v3, v2, v3
	v_fma_f32 v3, v2, v3, v2
	v_mul_f32_e32 v3, 0x3f4c422a, v3
	v_add_f32_e32 v3, v3, v3
	v_mul_f32_e32 v3, 0x3fb8aa3b, v3
	v_exp_f32_e32 v3, v3
	v_mul_f32_e32 v2, 0.5, v2
	v_add_f32_e32 v0, v5, v0
	v_add_f32_e32 v3, 1.0, v3
	v_div_scale_f32 v4, s[18:19], v3, v3, 2.0
	v_rcp_f32_e32 v6, v4
	s_nop 0
	v_fma_f32 v7, -v4, v6, 1.0
	v_fmac_f32_e32 v6, v7, v6
	v_div_scale_f32 v7, vcc, 2.0, v3, 2.0
	v_mul_f32_e32 v8, v7, v6
	v_fma_f32 v9, -v4, v8, v7
	v_fmac_f32_e32 v8, v9, v6
	v_fma_f32 v4, -v4, v8, v7
	v_div_fmas_f32 v4, v4, v6, v8
	v_div_fixup_f32 v3, v4, v3, 2.0
	v_sub_f32_e32 v3, 1.0, v3
	v_add_f32_e32 v3, 1.0, v3
	v_mul_f32_e32 v2, v2, v3
	v_cvt_pk_bf16_f32 v2, v2, s0
	ds_write_b16 v231, v2 offset:37952
	v_mul_f32_e32 v2, 0x3d372713, v0
	v_mul_f32_e32 v2, v0, v2
	v_fma_f32 v2, v0, v2, v0
	v_mul_f32_e32 v2, 0x3f4c422a, v2
	v_add_f32_e32 v2, v2, v2
	v_mul_f32_e32 v2, 0x3fb8aa3b, v2
	v_exp_f32_e32 v2, v2
	v_mul_f32_e32 v0, 0.5, v0
	v_add_f32_e32 v2, 1.0, v2
	v_div_scale_f32 v3, s[18:19], v2, v2, 2.0
	v_rcp_f32_e32 v4, v3
	s_nop 0
	v_fma_f32 v5, -v3, v4, 1.0
	v_fmac_f32_e32 v4, v5, v4
	v_div_scale_f32 v5, vcc, 2.0, v2, 2.0
	v_mul_f32_e32 v6, v5, v4
	v_fma_f32 v7, -v3, v6, v5
	v_fmac_f32_e32 v6, v7, v4
	v_fma_f32 v3, -v3, v6, v5
	v_div_fmas_f32 v3, v3, v4, v6
	v_div_fixup_f32 v2, v3, v2, 2.0
	v_sub_f32_e32 v2, 1.0, v2
	v_add_f32_e32 v2, 1.0, v2
	v_mul_f32_e32 v0, v0, v2
	v_cvt_pk_bf16_f32 v0, v0, s0
	s_and_b64 vcc, exec, s[10:11]
	ds_write_b16 v231, v0 offset:38480
	s_waitcnt lgkmcnt(0)
	s_barrier
	s_cbranch_vccz .LBB0_274
	s_and_b64 s[18:19], s[20:21], exec
	s_mov_b32 s14, 0x5d00000
	s_cselect_b32 s16, s14, 0x5d10000
	v_lshl_add_u64 v[14:15], v[132:133], 0, s[16:17]
	global_load_dwordx4 v[18:21], v[14:15], off
	global_load_dwordx4 v[22:25], v[14:15], off offset:64
	global_load_dwordx4 v[26:29], v[14:15], off offset:128
	global_load_dwordx4 v[30:33], v[14:15], off offset:192
	global_load_dwordx4 v[34:37], v[14:15], off offset:256
	global_load_dwordx4 v[38:41], v[14:15], off offset:320
	global_load_dwordx4 v[42:45], v[14:15], off offset:384
	global_load_dwordx4 v[46:49], v[14:15], off offset:448
	ds_read_b128 v[50:53], v229 offset:36864
	ds_read_b128 v[54:57], v229 offset:36928
	ds_read_b128 v[58:61], v229 offset:36992
	ds_read_b128 v[62:65], v229 offset:37056
	ds_read_b128 v[66:69], v229 offset:37120
	ds_read_b128 v[70:73], v229 offset:37184
	ds_read_b128 v[74:77], v229 offset:37248
	ds_read_b128 v[78:81], v229 offset:37312
	s_mov_b32 s14, 0x5e00000
	s_cselect_b32 s20, s14, 0x5e40000
	s_mov_b32 s21, s17
	s_lshl_b32 s4, s4, 15
	s_waitcnt vmcnt(7) lgkmcnt(7)
	v_mfma_f32_16x16x32_bf16 v[2:5], v[50:53], v[18:21], 0
	s_waitcnt vmcnt(6) lgkmcnt(6)
	v_mfma_f32_16x16x32_bf16 v[2:5], v[54:57], v[22:25], v[2:5]
	s_waitcnt vmcnt(5) lgkmcnt(5)
	v_mfma_f32_16x16x32_bf16 v[2:5], v[58:61], v[26:29], v[2:5]
	s_waitcnt vmcnt(4) lgkmcnt(4)
	v_mfma_f32_16x16x32_bf16 v[2:5], v[62:65], v[30:33], v[2:5]
	s_waitcnt vmcnt(3) lgkmcnt(3)
	v_mfma_f32_16x16x32_bf16 v[2:5], v[66:69], v[34:37], v[2:5]
	s_waitcnt vmcnt(2) lgkmcnt(2)
	v_mfma_f32_16x16x32_bf16 v[2:5], v[70:73], v[38:41], v[2:5]
	s_waitcnt vmcnt(1) lgkmcnt(1)
	v_mfma_f32_16x16x32_bf16 v[2:5], v[74:77], v[42:45], v[2:5]
	s_waitcnt vmcnt(0) lgkmcnt(0)
	v_mfma_f32_16x16x32_bf16 v[2:5], v[78:81], v[46:49], v[2:5]
	v_lshl_or_b32 v8, s5, 4, v216
	v_lshl_add_u64 v[6:7], v[134:135], 0, s[20:21]
	v_lshl_or_b32 v0, v8, 7, s4
	v_lshl_add_u64 v[6:7], v[6:7], 0, v[0:1]
	s_nop 3
	v_cvt_pk_bf16_f32 v0, v3, s0
	global_store_short v[6:7], v0, off offset:128
	v_cvt_pk_bf16_f32 v0, v4, s0
	s_movk_i32 s4, 0xfc
	global_store_short v[6:7], v0, off offset:256
	v_cvt_pk_bf16_f32 v0, v5, s0
	v_cmp_ne_u32_e32 vcc, s4, v8
	v_cvt_pk_bf16_f32 v2, v2, s0
	global_store_short v[6:7], v2, off
	v_cndmask_b32_e32 v0, 0, v0, vcc
	global_store_short v[6:7], v0, off offset:384

.LBB0_607:
	v_readlane_b32 s6, v253, 4
	v_readlane_b32 s7, v253, 5
	v_lshrrev_b32_e32 v135, 1, v146
	s_load_dwordx2 s[22:23], s[6:7], 0x98
	v_and_b32_e32 v136, 1, v146
	v_lshl_add_u32 v134, s5, 8, v135
	v_lshlrev_b32_e32 v134, 7, v134
	v_lshl_or_b32 v134, v136, 6, v134
	v_lshl_add_u32 v162, s5, 8, v149
	v_lshl_or_b32 v164, s4, 7, v177
	s_waitcnt lgkmcnt(0)
	s_add_u32 s4, s22, 0x1a700000
	s_addc_u32 s5, s23, 0
	global_load_dwordx4 v[236:239], v134, s[4:5]
	global_load_dwordx4 v[240:243], v134, s[4:5] offset:16
	global_load_dwordx4 v[244:247], v134, s[4:5] offset:32
	global_load_dwordx4 v[194:197], v134, s[4:5] offset:48
	s_mov_b32 s18, 0xf800000
	v_ashrrev_i32_e32 v165, 31, v164
	v_or_b32_e32 v168, 16, v162
	v_or_b32_e32 v166, 32, v162
	v_or_b32_e32 v170, 48, v162
	v_add_u32_e32 v172, 0x80, v162
	v_add_u32_e32 v184, 0x90, v162
	v_add_u32_e32 v188, 0xa0, v162
	v_add_u32_e32 v192, 0xb0, v162
	v_lshl_add_u64 v[132:133], v[164:165], 1, s[22:23]
	v_lshlrev_b32_e32 v135, 2, v135
	v_add_u32_e32 v135, 0x20240, v135
	s_waitcnt vmcnt(0)
	v_pk_add_f32 v[238:239], v[238:239], v[242:243]
	v_pk_add_f32 v[236:237], v[236:237], v[240:241]
	v_pk_add_f32 v[246:247], v[246:247], v[196:197]
	v_pk_add_f32 v[244:245], v[244:245], v[194:195]
	s_mov_b64 s[4:5], 0x12f00000
	v_add_f32_e32 v236, v236, v237
	v_add_f32_e32 v238, v238, v239
	v_add_f32_e32 v244, v244, v245
	v_add_f32_e32 v246, v246, v247
	v_add_f32_e32 v236, v236, v238
	v_add_f32_e32 v244, v244, v246
	v_lshl_add_u64 v[132:133], v[132:133], 0, s[4:5]
	v_add_f32_e32 v236, v236, v244
	s_nop 1
	v_mov_b32_dpp v237, v236 quad_perm:[1,0,3,2] row_mask:0xf bank_mask:0xf
	s_nop 0
	v_add_f32_e32 v236, v236, v237
	v_fmamk_f32 v137, v236, 0x3a000000, v204
	v_cmp_gt_f32_e32 vcc, s18, v137
	v_mul_f32_e32 v154, 0x4f800000, v137
	s_nop 0
	v_cndmask_b32_e32 v137, v137, v154, vcc
	v_sqrt_f32_e32 v154, v137
	s_nop 0
	v_add_u32_e32 v155, -1, v154
	v_fma_f32 v156, -v155, v154, v137
	v_cmp_ge_f32_e64 s[6:7], 0, v156
	v_add_u32_e32 v156, 1, v154
	s_nop 0
	v_cndmask_b32_e64 v155, v154, v155, s[6:7]
	v_fma_f32 v154, -v156, v154, v137
	v_cmp_lt_f32_e64 s[6:7], 0, v154
	s_nop 1
	v_cndmask_b32_e64 v154, v155, v156, s[6:7]
	v_mul_f32_e32 v155, 0x37800000, v154
	v_cndmask_b32_e32 v154, v154, v155, vcc
	v_cmp_class_f32_e32 vcc, v137, v205
	s_nop 1
	v_cndmask_b32_e32 v137, v154, v137, vcc
	v_div_scale_f32 v154, s[4:5], v137, v137, 1.0
	v_rcp_f32_e32 v155, v154
	s_nop 0
	v_fma_f32 v156, -v154, v155, 1.0
	v_fmac_f32_e32 v155, v156, v155
	v_div_scale_f32 v156, vcc, 1.0, v137, 1.0
	v_mul_f32_e32 v157, v156, v155
	v_fma_f32 v198, -v154, v157, v156
	v_fmac_f32_e32 v157, v198, v155
	v_fma_f32 v154, -v154, v157, v156
	v_div_fmas_f32 v154, v154, v155, v157
	v_div_fixup_f32 v199, v154, v137, 1.0
	ds_write_b32 v135, v199
	v_lshlrev_b32_e32 v134, 2, v149
	v_add_u32_e32 v134, 0x20240, v134
	s_waitcnt lgkmcnt(0)
	s_barrier
	ds_read_b32 v180, v134
	ds_read_b32 v176, v134 offset:64
	ds_read_b32 v174, v134 offset:128
	ds_read_b32 v178, v134 offset:192
	ds_read_b32 v182, v134 offset:512
	ds_read_b32 v186, v134 offset:576
	ds_read_b32 v190, v134 offset:640
	ds_read_b32 v130, v134 offset:704
	s_movk_i32 s6, 0x2c00
	s_waitcnt lgkmcnt(0)
	v_pk_mul_f32 v[126:127], v[126:127], v[180:181] op_sel_hi:[1,0]
	v_pk_mul_f32 v[118:119], v[118:119], v[180:181] op_sel_hi:[1,0]
	v_pk_mul_f32 v[128:129], v[128:129], v[180:181] op_sel_hi:[1,0]
	v_pk_mul_f32 v[120:121], v[120:121], v[180:181] op_sel_hi:[1,0]
	v_pk_mul_f32 v[122:123], v[122:123], v[180:181] op_sel_hi:[1,0]
	v_pk_mul_f32 v[124:125], v[124:125], v[180:181] op_sel_hi:[1,0]
	v_pk_mul_f32 v[110:111], v[110:111], v[176:177] op_sel_hi:[1,0]
	v_pk_mul_f32 v[102:103], v[102:103], v[176:177] op_sel_hi:[1,0]
	v_pk_mul_f32 v[112:113], v[112:113], v[176:177] op_sel_hi:[1,0]
	v_pk_mul_f32 v[104:105], v[104:105], v[176:177] op_sel_hi:[1,0]
	v_pk_mul_f32 v[106:107], v[106:107], v[176:177] op_sel_hi:[1,0]
	v_pk_mul_f32 v[108:109], v[108:109], v[176:177] op_sel_hi:[1,0]
	v_pk_mul_f32 v[94:95], v[94:95], v[174:175] op_sel_hi:[1,0]
	v_pk_mul_f32 v[86:87], v[86:87], v[174:175] op_sel_hi:[1,0]
	v_pk_mul_f32 v[96:97], v[96:97], v[174:175] op_sel_hi:[1,0]
	v_pk_mul_f32 v[88:89], v[88:89], v[174:175] op_sel_hi:[1,0]
	v_pk_mul_f32 v[90:91], v[90:91], v[174:175] op_sel_hi:[1,0]
	v_pk_mul_f32 v[92:93], v[92:93], v[174:175] op_sel_hi:[1,0]
	v_pk_mul_f32 v[78:79], v[78:79], v[178:179] op_sel_hi:[1,0]
	v_pk_mul_f32 v[70:71], v[70:71], v[178:179] op_sel_hi:[1,0]
	v_pk_mul_f32 v[80:81], v[80:81], v[178:179] op_sel_hi:[1,0]
	v_pk_mul_f32 v[72:73], v[72:73], v[178:179] op_sel_hi:[1,0]
	v_pk_mul_f32 v[74:75], v[74:75], v[178:179] op_sel_hi:[1,0]
	v_pk_mul_f32 v[76:77], v[76:77], v[178:179] op_sel_hi:[1,0]
	v_pk_mul_f32 v[62:63], v[62:63], v[182:183] op_sel_hi:[1,0]
	v_pk_mul_f32 v[54:55], v[54:55], v[182:183] op_sel_hi:[1,0]
	v_pk_mul_f32 v[64:65], v[64:65], v[182:183] op_sel_hi:[1,0]
	v_pk_mul_f32 v[56:57], v[56:57], v[182:183] op_sel_hi:[1,0]
	v_pk_mul_f32 v[58:59], v[58:59], v[182:183] op_sel_hi:[1,0]
	v_pk_mul_f32 v[60:61], v[60:61], v[182:183] op_sel_hi:[1,0]
	v_pk_mul_f32 v[46:47], v[46:47], v[186:187] op_sel_hi:[1,0]
	v_pk_mul_f32 v[38:39], v[38:39], v[186:187] op_sel_hi:[1,0]
	v_pk_mul_f32 v[48:49], v[48:49], v[186:187] op_sel_hi:[1,0]
	v_pk_mul_f32 v[40:41], v[40:41], v[186:187] op_sel_hi:[1,0]
	v_pk_mul_f32 v[42:43], v[42:43], v[186:187] op_sel_hi:[1,0]
	v_pk_mul_f32 v[44:45], v[44:45], v[186:187] op_sel_hi:[1,0]
	v_pk_mul_f32 v[30:31], v[30:31], v[190:191] op_sel_hi:[1,0]
	v_pk_mul_f32 v[22:23], v[22:23], v[190:191] op_sel_hi:[1,0]
	v_pk_mul_f32 v[32:33], v[32:33], v[190:191] op_sel_hi:[1,0]
	v_pk_mul_f32 v[24:25], v[24:25], v[190:191] op_sel_hi:[1,0]
	v_pk_mul_f32 v[26:27], v[26:27], v[190:191] op_sel_hi:[1,0]
	v_pk_mul_f32 v[28:29], v[28:29], v[190:191] op_sel_hi:[1,0]
	v_pk_mul_f32 v[136:137], v[116:117], v[180:181] op_sel_hi:[1,0]
	v_pk_mul_f32 v[116:117], v[114:115], v[180:181] op_sel_hi:[1,0]
	v_mul_f32_e32 v114, 0xbfb8aa3b, v126
	v_mul_f32_e32 v115, 0xbfb8aa3b, v127
	v_exp_f32_e32 v114, v114
	v_exp_f32_e32 v115, v115
	v_mad_i64_i32 v[134:135], s[4:5], v162, s6, v[132:133]
	v_add_f32_e32 v114, 1.0, v114
	v_add_f32_e32 v115, 1.0, v115
	v_rcp_f32_e32 v114, v114
	v_rcp_f32_e32 v115, v115
	s_nop 0
	v_pk_mul_f32 v[114:115], v[126:127], v[114:115]
	s_nop 0
	v_pk_mul_f32 v[114:115], v[118:119], v[114:115]
	s_nop 0
	v_cvt_pk_bf16_f32 v114, v114, v115
	v_mul_f32_e32 v115, 0xbfb8aa3b, v128
	v_exp_f32_e32 v115, v115
	s_nop 0
	v_add_f32_e32 v115, 1.0, v115
	v_rcp_f32_e32 v118, v115
	v_mul_f32_e32 v115, 0xbfb8aa3b, v129
	v_exp_f32_e32 v115, v115
	s_nop 0
	v_add_f32_e32 v115, 1.0, v115
	v_rcp_f32_e32 v119, v115
	s_nop 0
	v_pk_mul_f32 v[118:119], v[128:129], v[118:119]
	s_nop 0
	v_pk_mul_f32 v[118:119], v[120:121], v[118:119]
	s_nop 0
	v_cvt_pk_bf16_f32 v115, v118, v119
	v_mul_f32_e32 v118, 0xbfb8aa3b, v122
	v_mul_f32_e32 v119, 0xbfb8aa3b, v123
	v_exp_f32_e32 v118, v118
	v_exp_f32_e32 v119, v119
	s_nop 0
	v_add_f32_e32 v118, 1.0, v118
	v_add_f32_e32 v119, 1.0, v119
	v_rcp_f32_e32 v118, v118
	v_rcp_f32_e32 v119, v119
	s_nop 0
	v_pk_mul_f32 v[118:119], v[122:123], v[118:119]
	s_nop 0
	v_pk_mul_f32 v[116:117], v[116:117], v[118:119]
	s_nop 0
	v_cvt_pk_bf16_f32 v116, v116, v117
	v_mul_f32_e32 v117, 0xbfb8aa3b, v124
	v_exp_f32_e32 v117, v117
	s_nop 0
	v_add_f32_e32 v117, 1.0, v117
	v_rcp_f32_e32 v118, v117
	v_mul_f32_e32 v117, 0xbfb8aa3b, v125
	v_exp_f32_e32 v117, v117
	s_nop 0
	v_add_f32_e32 v117, 1.0, v117
	v_rcp_f32_e32 v119, v117
	s_nop 0
	v_pk_mul_f32 v[118:119], v[124:125], v[118:119]
	s_nop 0
	v_pk_mul_f32 v[118:119], v[136:137], v[118:119]
	s_nop 0
	v_cvt_pk_bf16_f32 v117, v118, v119
	global_store_dwordx4 v[134:135], v[114:117], off sc1
	s_nop 1
	v_pk_mul_f32 v[14:15], v[14:15], v[130:131] op_sel_hi:[1,0]
	v_pk_mul_f32 v[116:117], v[100:101], v[176:177] op_sel_hi:[1,0]
	v_pk_mul_f32 v[100:101], v[98:99], v[176:177] op_sel_hi:[1,0]
	v_mul_f32_e32 v98, 0xbfb8aa3b, v110
	v_mul_f32_e32 v99, 0xbfb8aa3b, v111
	v_exp_f32_e32 v98, v98
	v_exp_f32_e32 v99, v99
	v_mad_i64_i32 v[114:115], s[4:5], v168, s6, v[132:133]
	v_add_f32_e32 v98, 1.0, v98
	v_add_f32_e32 v99, 1.0, v99
	v_rcp_f32_e32 v98, v98
	v_rcp_f32_e32 v99, v99
	v_pk_mul_f32 v[6:7], v[6:7], v[130:131] op_sel_hi:[1,0]
	v_pk_mul_f32 v[16:17], v[16:17], v[130:131] op_sel_hi:[1,0]
	v_pk_mul_f32 v[8:9], v[8:9], v[130:131] op_sel_hi:[1,0]
	v_pk_mul_f32 v[98:99], v[110:111], v[98:99]
	v_pk_mul_f32 v[10:11], v[10:11], v[130:131] op_sel_hi:[1,0]
	v_pk_mul_f32 v[98:99], v[102:103], v[98:99]
	v_pk_mul_f32 v[12:13], v[12:13], v[130:131] op_sel_hi:[1,0]
	v_cvt_pk_bf16_f32 v98, v98, v99
	v_mul_f32_e32 v99, 0xbfb8aa3b, v112
	v_exp_f32_e32 v99, v99
	s_andn2_b64 vcc, exec, s[38:39]
	v_add_f32_e32 v99, 1.0, v99
	v_rcp_f32_e32 v102, v99
	v_mul_f32_e32 v99, 0xbfb8aa3b, v113
	v_exp_f32_e32 v99, v99
	s_nop 0
	v_add_f32_e32 v99, 1.0, v99
	v_rcp_f32_e32 v103, v99
	s_nop 0
	v_pk_mul_f32 v[102:103], v[112:113], v[102:103]
	s_nop 0
	v_pk_mul_f32 v[102:103], v[104:105], v[102:103]
	s_nop 0
	v_cvt_pk_bf16_f32 v99, v102, v103
	v_mul_f32_e32 v102, 0xbfb8aa3b, v106
	v_mul_f32_e32 v103, 0xbfb8aa3b, v107
	v_exp_f32_e32 v102, v102
	v_exp_f32_e32 v103, v103
	v_add_f32_e32 v102, 1.0, v102
	v_add_f32_e32 v103, 1.0, v103
	v_rcp_f32_e32 v102, v102
	v_rcp_f32_e32 v103, v103
	s_nop 0
	v_pk_mul_f32 v[102:103], v[106:107], v[102:103]
	s_nop 0
	v_pk_mul_f32 v[100:101], v[100:101], v[102:103]
	s_nop 0
	v_cvt_pk_bf16_f32 v100, v100, v101
	v_mul_f32_e32 v101, 0xbfb8aa3b, v108
	v_exp_f32_e32 v101, v101
	s_nop 0
	v_add_f32_e32 v101, 1.0, v101
	v_rcp_f32_e32 v102, v101
	v_mul_f32_e32 v101, 0xbfb8aa3b, v109
	v_exp_f32_e32 v101, v101
	s_nop 0
	v_add_f32_e32 v101, 1.0, v101
	v_rcp_f32_e32 v103, v101
	s_nop 0
	v_pk_mul_f32 v[102:103], v[108:109], v[102:103]
	s_nop 0
	v_pk_mul_f32 v[102:103], v[116:117], v[102:103]
	s_nop 0
	v_cvt_pk_bf16_f32 v101, v102, v103
	global_store_dwordx4 v[114:115], v[98:101], off sc1
	s_nop 1
	v_pk_mul_f32 v[100:101], v[84:85], v[174:175] op_sel_hi:[1,0]
	v_pk_mul_f32 v[84:85], v[82:83], v[174:175] op_sel_hi:[1,0]
	v_mul_f32_e32 v82, 0xbfb8aa3b, v94
	v_mul_f32_e32 v83, 0xbfb8aa3b, v95
	v_exp_f32_e32 v82, v82
	v_exp_f32_e32 v83, v83
	v_mad_i64_i32 v[98:99], s[4:5], v166, s6, v[132:133]
	v_add_f32_e32 v82, 1.0, v82
	v_add_f32_e32 v83, 1.0, v83
	v_rcp_f32_e32 v82, v82
	v_rcp_f32_e32 v83, v83
	s_nop 0
	v_pk_mul_f32 v[82:83], v[94:95], v[82:83]
	s_nop 0
	v_pk_mul_f32 v[82:83], v[86:87], v[82:83]
	s_nop 0
	v_cvt_pk_bf16_f32 v82, v82, v83
	v_mul_f32_e32 v83, 0xbfb8aa3b, v96
	v_exp_f32_e32 v83, v83
	s_nop 0
	v_add_f32_e32 v83, 1.0, v83
	v_rcp_f32_e32 v86, v83
	v_mul_f32_e32 v83, 0xbfb8aa3b, v97
	v_exp_f32_e32 v83, v83
	s_nop 0
	v_add_f32_e32 v83, 1.0, v83
	v_rcp_f32_e32 v87, v83
	s_nop 0
	v_pk_mul_f32 v[86:87], v[96:97], v[86:87]
	s_nop 0
	v_pk_mul_f32 v[86:87], v[88:89], v[86:87]
	s_nop 0
	v_cvt_pk_bf16_f32 v83, v86, v87
	v_mul_f32_e32 v86, 0xbfb8aa3b, v90
	v_mul_f32_e32 v87, 0xbfb8aa3b, v91
	v_exp_f32_e32 v86, v86
	v_exp_f32_e32 v87, v87
	v_add_f32_e32 v86, 1.0, v86
	v_add_f32_e32 v87, 1.0, v87
	v_rcp_f32_e32 v86, v86
	v_rcp_f32_e32 v87, v87
	s_nop 0
	v_pk_mul_f32 v[86:87], v[90:91], v[86:87]
	s_nop 0
	v_pk_mul_f32 v[84:85], v[84:85], v[86:87]
	s_nop 0
	v_cvt_pk_bf16_f32 v84, v84, v85
	v_mul_f32_e32 v85, 0xbfb8aa3b, v92
	v_exp_f32_e32 v85, v85
	s_nop 0
	v_add_f32_e32 v85, 1.0, v85
	v_rcp_f32_e32 v86, v85
	v_mul_f32_e32 v85, 0xbfb8aa3b, v93
	v_exp_f32_e32 v85, v85
	s_nop 0
	v_add_f32_e32 v85, 1.0, v85
	v_rcp_f32_e32 v87, v85
	s_nop 0
	v_pk_mul_f32 v[86:87], v[92:93], v[86:87]
	s_nop 0
	v_pk_mul_f32 v[86:87], v[100:101], v[86:87]
	s_nop 0
	v_cvt_pk_bf16_f32 v85, v86, v87
	global_store_dwordx4 v[98:99], v[82:85], off sc1
	s_nop 1
	v_pk_mul_f32 v[84:85], v[68:69], v[178:179] op_sel_hi:[1,0]
	v_pk_mul_f32 v[68:69], v[66:67], v[178:179] op_sel_hi:[1,0]
	v_mul_f32_e32 v66, 0xbfb8aa3b, v78
	v_mul_f32_e32 v67, 0xbfb8aa3b, v79
	v_exp_f32_e32 v66, v66
	v_exp_f32_e32 v67, v67
	v_mad_i64_i32 v[82:83], s[4:5], v170, s6, v[132:133]
	v_add_f32_e32 v66, 1.0, v66
	v_add_f32_e32 v67, 1.0, v67
	v_rcp_f32_e32 v66, v66
	v_rcp_f32_e32 v67, v67
	s_nop 0
	v_pk_mul_f32 v[66:67], v[78:79], v[66:67]
	s_nop 0
	v_pk_mul_f32 v[66:67], v[70:71], v[66:67]
	s_nop 0
	v_cvt_pk_bf16_f32 v66, v66, v67
	v_mul_f32_e32 v67, 0xbfb8aa3b, v80
	v_exp_f32_e32 v67, v67
	s_nop 0
	v_add_f32_e32 v67, 1.0, v67
	v_rcp_f32_e32 v70, v67
	v_mul_f32_e32 v67, 0xbfb8aa3b, v81
	v_exp_f32_e32 v67, v67
	s_nop 0
	v_add_f32_e32 v67, 1.0, v67
	v_rcp_f32_e32 v71, v67
	s_nop 0
	v_pk_mul_f32 v[70:71], v[80:81], v[70:71]
	s_nop 0
	v_pk_mul_f32 v[70:71], v[72:73], v[70:71]
	s_nop 0
	v_cvt_pk_bf16_f32 v67, v70, v71
	v_mul_f32_e32 v70, 0xbfb8aa3b, v74
	v_mul_f32_e32 v71, 0xbfb8aa3b, v75
	v_exp_f32_e32 v70, v70
	v_exp_f32_e32 v71, v71
	v_add_f32_e32 v70, 1.0, v70
	v_add_f32_e32 v71, 1.0, v71
	v_rcp_f32_e32 v70, v70
	v_rcp_f32_e32 v71, v71
	s_nop 0
	v_pk_mul_f32 v[70:71], v[74:75], v[70:71]
	s_nop 0
	v_pk_mul_f32 v[68:69], v[68:69], v[70:71]
	s_nop 0
	v_cvt_pk_bf16_f32 v68, v68, v69
	v_mul_f32_e32 v69, 0xbfb8aa3b, v76
	v_exp_f32_e32 v69, v69
	s_nop 0
	v_add_f32_e32 v69, 1.0, v69
	v_rcp_f32_e32 v70, v69
	v_mul_f32_e32 v69, 0xbfb8aa3b, v77
	v_exp_f32_e32 v69, v69
	s_nop 0
	v_add_f32_e32 v69, 1.0, v69
	v_rcp_f32_e32 v71, v69
	s_nop 0
	v_pk_mul_f32 v[70:71], v[76:77], v[70:71]
	s_nop 0
	v_pk_mul_f32 v[70:71], v[84:85], v[70:71]
	s_nop 0
	v_cvt_pk_bf16_f32 v69, v70, v71
	global_store_dwordx4 v[82:83], v[66:69], off sc1
	s_nop 1
	v_pk_mul_f32 v[68:69], v[52:53], v[182:183] op_sel_hi:[1,0]
	v_pk_mul_f32 v[52:53], v[50:51], v[182:183] op_sel_hi:[1,0]
	v_mul_f32_e32 v50, 0xbfb8aa3b, v62
	v_mul_f32_e32 v51, 0xbfb8aa3b, v63
	v_exp_f32_e32 v50, v50
	v_exp_f32_e32 v51, v51
	v_mad_i64_i32 v[66:67], s[4:5], v172, s6, v[132:133]
	v_add_f32_e32 v50, 1.0, v50
	v_add_f32_e32 v51, 1.0, v51
	v_rcp_f32_e32 v50, v50
	v_rcp_f32_e32 v51, v51
	s_nop 0
	v_pk_mul_f32 v[50:51], v[62:63], v[50:51]
	s_nop 0
	v_pk_mul_f32 v[50:51], v[54:55], v[50:51]
	s_nop 0
	v_cvt_pk_bf16_f32 v50, v50, v51
	v_mul_f32_e32 v51, 0xbfb8aa3b, v64
	v_exp_f32_e32 v51, v51
	s_nop 0
	v_add_f32_e32 v51, 1.0, v51
	v_rcp_f32_e32 v54, v51
	v_mul_f32_e32 v51, 0xbfb8aa3b, v65
	v_exp_f32_e32 v51, v51
	s_nop 0
	v_add_f32_e32 v51, 1.0, v51
	v_rcp_f32_e32 v55, v51
	s_nop 0
	v_pk_mul_f32 v[54:55], v[64:65], v[54:55]
	s_nop 0
	v_pk_mul_f32 v[54:55], v[56:57], v[54:55]
	s_nop 0
	v_cvt_pk_bf16_f32 v51, v54, v55
	v_mul_f32_e32 v54, 0xbfb8aa3b, v58
	v_mul_f32_e32 v55, 0xbfb8aa3b, v59
	v_exp_f32_e32 v54, v54
	v_exp_f32_e32 v55, v55
	v_add_f32_e32 v54, 1.0, v54
	v_add_f32_e32 v55, 1.0, v55
	v_rcp_f32_e32 v54, v54
	v_rcp_f32_e32 v55, v55
	s_nop 0
	v_pk_mul_f32 v[54:55], v[58:59], v[54:55]
	s_nop 0
	v_pk_mul_f32 v[52:53], v[52:53], v[54:55]
	s_nop 0
	v_cvt_pk_bf16_f32 v52, v52, v53
	v_mul_f32_e32 v53, 0xbfb8aa3b, v60
	v_exp_f32_e32 v53, v53
	s_nop 0
	v_add_f32_e32 v53, 1.0, v53
	v_rcp_f32_e32 v54, v53
	v_mul_f32_e32 v53, 0xbfb8aa3b, v61
	v_exp_f32_e32 v53, v53
	s_nop 0
	v_add_f32_e32 v53, 1.0, v53
	v_rcp_f32_e32 v55, v53
	s_nop 0
	v_pk_mul_f32 v[54:55], v[60:61], v[54:55]
	s_nop 0
	v_pk_mul_f32 v[54:55], v[68:69], v[54:55]
	s_nop 0
	v_cvt_pk_bf16_f32 v53, v54, v55
	global_store_dwordx4 v[66:67], v[50:53], off sc1
	s_nop 1
	v_pk_mul_f32 v[52:53], v[36:37], v[186:187] op_sel_hi:[1,0]
	v_pk_mul_f32 v[36:37], v[34:35], v[186:187] op_sel_hi:[1,0]
	v_mul_f32_e32 v34, 0xbfb8aa3b, v46
	v_mul_f32_e32 v35, 0xbfb8aa3b, v47
	v_exp_f32_e32 v34, v34
	v_exp_f32_e32 v35, v35
	v_mad_i64_i32 v[50:51], s[4:5], v184, s6, v[132:133]
	v_add_f32_e32 v34, 1.0, v34
	v_add_f32_e32 v35, 1.0, v35
	v_rcp_f32_e32 v34, v34
	v_rcp_f32_e32 v35, v35
	s_nop 0
	v_pk_mul_f32 v[34:35], v[46:47], v[34:35]
	s_nop 0
	v_pk_mul_f32 v[34:35], v[38:39], v[34:35]
	s_nop 0
	v_cvt_pk_bf16_f32 v34, v34, v35
	v_mul_f32_e32 v35, 0xbfb8aa3b, v48
	v_exp_f32_e32 v35, v35
	s_nop 0
	v_add_f32_e32 v35, 1.0, v35
	v_rcp_f32_e32 v38, v35
	v_mul_f32_e32 v35, 0xbfb8aa3b, v49
	v_exp_f32_e32 v35, v35
	s_nop 0
	v_add_f32_e32 v35, 1.0, v35
	v_rcp_f32_e32 v39, v35
	s_nop 0
	v_pk_mul_f32 v[38:39], v[48:49], v[38:39]
	s_nop 0
	v_pk_mul_f32 v[38:39], v[40:41], v[38:39]
	s_nop 0
	v_cvt_pk_bf16_f32 v35, v38, v39
	v_mul_f32_e32 v38, 0xbfb8aa3b, v42
	v_mul_f32_e32 v39, 0xbfb8aa3b, v43
	v_exp_f32_e32 v38, v38
	v_exp_f32_e32 v39, v39
	v_add_f32_e32 v38, 1.0, v38
	v_add_f32_e32 v39, 1.0, v39
	v_rcp_f32_e32 v38, v38
	v_rcp_f32_e32 v39, v39
	s_nop 0
	v_pk_mul_f32 v[38:39], v[42:43], v[38:39]
	s_nop 0
	v_pk_mul_f32 v[36:37], v[36:37], v[38:39]
	s_nop 0
	v_cvt_pk_bf16_f32 v36, v36, v37
	v_mul_f32_e32 v37, 0xbfb8aa3b, v44
	v_exp_f32_e32 v37, v37
	s_nop 0
	v_add_f32_e32 v37, 1.0, v37
	v_rcp_f32_e32 v38, v37
	v_mul_f32_e32 v37, 0xbfb8aa3b, v45
	v_exp_f32_e32 v37, v37
	s_nop 0
	v_add_f32_e32 v37, 1.0, v37
	v_rcp_f32_e32 v39, v37
	s_nop 0
	v_pk_mul_f32 v[38:39], v[44:45], v[38:39]
	s_nop 0
	v_pk_mul_f32 v[38:39], v[52:53], v[38:39]
	s_nop 0
	v_cvt_pk_bf16_f32 v37, v38, v39
	global_store_dwordx4 v[50:51], v[34:37], off sc1
	s_nop 1
	v_pk_mul_f32 v[36:37], v[20:21], v[190:191] op_sel_hi:[1,0]
	v_pk_mul_f32 v[20:21], v[18:19], v[190:191] op_sel_hi:[1,0]
	v_mul_f32_e32 v18, 0xbfb8aa3b, v30
	v_mul_f32_e32 v19, 0xbfb8aa3b, v31
	v_exp_f32_e32 v18, v18
	v_exp_f32_e32 v19, v19
	v_mad_i64_i32 v[34:35], s[4:5], v188, s6, v[132:133]
	v_add_f32_e32 v18, 1.0, v18
	v_add_f32_e32 v19, 1.0, v19
	v_rcp_f32_e32 v18, v18
	v_rcp_f32_e32 v19, v19
	s_nop 0
	v_pk_mul_f32 v[18:19], v[30:31], v[18:19]
	s_nop 0
	v_pk_mul_f32 v[18:19], v[22:23], v[18:19]
	s_nop 0
	v_cvt_pk_bf16_f32 v18, v18, v19
	v_mul_f32_e32 v19, 0xbfb8aa3b, v32
	v_exp_f32_e32 v19, v19
	s_nop 0
	v_add_f32_e32 v19, 1.0, v19
	v_rcp_f32_e32 v22, v19
	v_mul_f32_e32 v19, 0xbfb8aa3b, v33
	v_exp_f32_e32 v19, v19
	s_nop 0
	v_add_f32_e32 v19, 1.0, v19
	v_rcp_f32_e32 v23, v19
	s_nop 0
	v_pk_mul_f32 v[22:23], v[32:33], v[22:23]
	s_nop 0
	v_pk_mul_f32 v[22:23], v[24:25], v[22:23]
	s_nop 0
	v_cvt_pk_bf16_f32 v19, v22, v23
	v_mul_f32_e32 v22, 0xbfb8aa3b, v26
	v_mul_f32_e32 v23, 0xbfb8aa3b, v27
	v_exp_f32_e32 v22, v22
	v_exp_f32_e32 v23, v23
	v_add_f32_e32 v22, 1.0, v22
	v_add_f32_e32 v23, 1.0, v23
	v_rcp_f32_e32 v22, v22
	v_rcp_f32_e32 v23, v23
	s_nop 0
	v_pk_mul_f32 v[22:23], v[26:27], v[22:23]
	s_nop 0
	v_pk_mul_f32 v[20:21], v[20:21], v[22:23]
	s_nop 0
	v_cvt_pk_bf16_f32 v20, v20, v21
	v_mul_f32_e32 v21, 0xbfb8aa3b, v28
	v_exp_f32_e32 v21, v21
	s_nop 0
	v_add_f32_e32 v21, 1.0, v21
	v_rcp_f32_e32 v22, v21
	v_mul_f32_e32 v21, 0xbfb8aa3b, v29
	v_exp_f32_e32 v21, v21
	s_nop 0
	v_add_f32_e32 v21, 1.0, v21
	v_rcp_f32_e32 v23, v21
	s_nop 0
	v_pk_mul_f32 v[22:23], v[28:29], v[22:23]
	s_nop 0
	v_pk_mul_f32 v[22:23], v[36:37], v[22:23]
	s_nop 0
	v_cvt_pk_bf16_f32 v21, v22, v23
	global_store_dwordx4 v[34:35], v[18:21], off sc1
	s_nop 1
	v_pk_mul_f32 v[20:21], v[4:5], v[130:131] op_sel_hi:[1,0]
	v_pk_mul_f32 v[4:5], v[2:3], v[130:131] op_sel_hi:[1,0]
	v_mul_f32_e32 v2, 0xbfb8aa3b, v14
	v_mul_f32_e32 v3, 0xbfb8aa3b, v15
	v_exp_f32_e32 v2, v2
	v_exp_f32_e32 v3, v3
	v_mad_i64_i32 v[18:19], s[4:5], v192, s6, v[132:133]
	v_add_f32_e32 v2, 1.0, v2
	v_add_f32_e32 v3, 1.0, v3
	v_rcp_f32_e32 v2, v2
	v_rcp_f32_e32 v3, v3
	s_mov_b64 s[6:7], -1
	v_pk_mul_f32 v[2:3], v[14:15], v[2:3]
	s_nop 0
	v_pk_mul_f32 v[2:3], v[6:7], v[2:3]
	s_nop 0
	v_cvt_pk_bf16_f32 v2, v2, v3
	v_mul_f32_e32 v3, 0xbfb8aa3b, v16
	v_exp_f32_e32 v3, v3
	s_nop 0
	v_add_f32_e32 v3, 1.0, v3
	v_rcp_f32_e32 v6, v3
	v_mul_f32_e32 v3, 0xbfb8aa3b, v17
	v_exp_f32_e32 v3, v3
	s_nop 0
	v_add_f32_e32 v3, 1.0, v3
	v_rcp_f32_e32 v7, v3
	s_nop 0
	v_pk_mul_f32 v[6:7], v[16:17], v[6:7]
	s_nop 0
	v_pk_mul_f32 v[6:7], v[8:9], v[6:7]
	s_nop 0
	v_cvt_pk_bf16_f32 v3, v6, v7
	v_mul_f32_e32 v6, 0xbfb8aa3b, v10
	v_mul_f32_e32 v7, 0xbfb8aa3b, v11
	v_exp_f32_e32 v6, v6
	v_exp_f32_e32 v7, v7
	v_add_f32_e32 v6, 1.0, v6
	v_add_f32_e32 v7, 1.0, v7
	v_rcp_f32_e32 v6, v6
	v_rcp_f32_e32 v7, v7
	s_nop 0
	v_pk_mul_f32 v[6:7], v[10:11], v[6:7]
	s_nop 0
	v_pk_mul_f32 v[4:5], v[4:5], v[6:7]
	s_nop 0
	v_cvt_pk_bf16_f32 v4, v4, v5
	v_mul_f32_e32 v5, 0xbfb8aa3b, v12
	v_exp_f32_e32 v5, v5
	s_nop 0
	v_add_f32_e32 v5, 1.0, v5
	v_rcp_f32_e32 v6, v5
	v_mul_f32_e32 v5, 0xbfb8aa3b, v13
	v_exp_f32_e32 v5, v5
	s_nop 0
	v_add_f32_e32 v5, 1.0, v5
	v_rcp_f32_e32 v7, v5
	s_nop 0
	v_pk_mul_f32 v[6:7], v[12:13], v[6:7]
	s_nop 0
	v_pk_mul_f32 v[6:7], v[20:21], v[6:7]
	s_nop 0
	v_cvt_pk_bf16_f32 v5, v6, v7
	global_store_dwordx4 v[18:19], v[2:5], off sc1
	s_cbranch_vccnz .LBB0_600
	s_andn2_b64 vcc, exec, s[10:11]
	s_cbranch_vccnz .LBB0_599
	s_barrier
	s_branch .LBB0_599
